# softmax in base 2: log2(e) folded into the attention q scale constants (gemm1 and cross-q epilogues), per-element multiply removed; dil LSE converted back with ln2; widened rwkv-front stores
# speedup vs baseline: 1.0620x; 1.0044x over previous
.LBB0_241:
	s_add_i32 s41, s41, 1
	s_add_u32 s25, s50, s28
	s_addc_u32 s27, s51, s29
	s_lshl_b32 s0, s24, 8
	s_ashr_i32 s1, s0, 31
	s_mov_b32 s24, 0x3fff80
	s_lshl_b64 s[0:1], s[0:1], 1
	s_add_u32 s0, s25, s0
	s_addc_u32 s1, s27, s1
	v_lshrrev_b32_e32 v248, 1, v166
	v_and_b32_e32 v248, 0x80, v248
	v_and_b32_e32 v249, 15, v166
	v_or_b32_e32 v248, v248, v249
	v_and_b32_e32 v249, 16, v166
	v_lshrrev_b32_e32 v250, 2, v166
	v_and_b32_e32 v250, 8, v250
	v_or_b32_e32 v249, v249, v250
	v_and_b32_e32 v250, 0xc0, v166
	v_or_b32_e32 v249, v249, v250
	v_lshl_or_b32 v248, v248, 10, v249
	v_mov_b32_e32 v249, 0
	v_lshl_add_u64 v[246:247], v[248:249], 1, s[0:1]
	v_cvt_pk_bf16_f32 v126, v126, v127
	v_cvt_pk_bf16_f32 v127, v128, v129
	v_cvt_pk_bf16_f32 v128, v122, v123
	v_cvt_pk_bf16_f32 v129, v124, v125
	v_cvt_pk_bf16_f32 v118, v118, v119
	v_cvt_pk_bf16_f32 v119, v120, v121
	v_cvt_pk_bf16_f32 v120, v114, v115
	v_cvt_pk_bf16_f32 v121, v116, v117
	s_nop 1
	v_permlane16_swap_b32_e32 v126, v128
	v_permlane16_swap_b32_e32 v127, v129
	v_permlane16_swap_b32_e32 v118, v120
	v_permlane16_swap_b32_e32 v119, v121
	global_store_dwordx4 v[246:247], v[126:129], off
	global_store_dwordx4 v[246:247], v[118:121], off offset:64
	v_add_co_u32_e32 v246, vcc, 0x8000, v246
	s_nop 1
	v_addc_co_u32_e32 v247, vcc, 0, v247, vcc
	v_cvt_pk_bf16_f32 v110, v110, v111
	v_cvt_pk_bf16_f32 v111, v112, v113
	v_cvt_pk_bf16_f32 v112, v106, v107
	v_cvt_pk_bf16_f32 v113, v108, v109
	v_cvt_pk_bf16_f32 v102, v102, v103
	v_cvt_pk_bf16_f32 v103, v104, v105
	v_cvt_pk_bf16_f32 v104, v98, v99
	v_cvt_pk_bf16_f32 v105, v100, v101
	s_nop 1
	v_permlane16_swap_b32_e32 v110, v112
	v_permlane16_swap_b32_e32 v111, v113
	v_permlane16_swap_b32_e32 v102, v104
	v_permlane16_swap_b32_e32 v103, v105
	global_store_dwordx4 v[246:247], v[110:113], off
	global_store_dwordx4 v[246:247], v[102:105], off offset:64
	v_add_co_u32_e32 v246, vcc, 0x8000, v246
	s_nop 1
	v_addc_co_u32_e32 v247, vcc, 0, v247, vcc
	v_cvt_pk_bf16_f32 v94, v94, v95
	v_cvt_pk_bf16_f32 v95, v96, v97
	v_cvt_pk_bf16_f32 v96, v90, v91
	v_cvt_pk_bf16_f32 v97, v92, v93
	v_cvt_pk_bf16_f32 v86, v86, v87
	v_cvt_pk_bf16_f32 v87, v88, v89
	v_cvt_pk_bf16_f32 v88, v82, v83
	v_cvt_pk_bf16_f32 v89, v84, v85
	s_nop 1
	v_permlane16_swap_b32_e32 v94, v96
	v_permlane16_swap_b32_e32 v95, v97
	v_permlane16_swap_b32_e32 v86, v88
	v_permlane16_swap_b32_e32 v87, v89
	global_store_dwordx4 v[246:247], v[94:97], off
	global_store_dwordx4 v[246:247], v[86:89], off offset:64
	v_add_co_u32_e32 v246, vcc, 0x8000, v246
	s_nop 1
	v_addc_co_u32_e32 v247, vcc, 0, v247, vcc
	v_cvt_pk_bf16_f32 v78, v78, v79
	v_cvt_pk_bf16_f32 v79, v80, v81
	v_cvt_pk_bf16_f32 v80, v74, v75
	v_cvt_pk_bf16_f32 v81, v76, v77
	v_cvt_pk_bf16_f32 v70, v70, v71
	v_cvt_pk_bf16_f32 v71, v72, v73
	v_cvt_pk_bf16_f32 v72, v66, v67
	v_cvt_pk_bf16_f32 v73, v68, v69
	s_nop 1
	v_permlane16_swap_b32_e32 v78, v80
	v_permlane16_swap_b32_e32 v79, v81
	v_permlane16_swap_b32_e32 v70, v72
	v_permlane16_swap_b32_e32 v71, v73
	global_store_dwordx4 v[246:247], v[78:81], off
	global_store_dwordx4 v[246:247], v[70:73], off offset:64
	v_add_co_u32_e32 v246, vcc, 0x8000, v246
	s_nop 1
	v_addc_co_u32_e32 v247, vcc, 0, v247, vcc
	v_cvt_pk_bf16_f32 v60, v60, v61
	v_cvt_pk_bf16_f32 v61, v62, v63
	v_cvt_pk_bf16_f32 v62, v56, v57
	v_cvt_pk_bf16_f32 v63, v58, v59
	v_cvt_pk_bf16_f32 v52, v52, v53
	v_cvt_pk_bf16_f32 v53, v54, v55
	v_cvt_pk_bf16_f32 v54, v48, v49
	v_cvt_pk_bf16_f32 v55, v50, v51
	s_nop 1
	v_permlane16_swap_b32_e32 v60, v62
	v_permlane16_swap_b32_e32 v61, v63
	v_permlane16_swap_b32_e32 v52, v54
	v_permlane16_swap_b32_e32 v53, v55
	global_store_dwordx4 v[246:247], v[60:63], off
	global_store_dwordx4 v[246:247], v[52:55], off offset:64
	v_add_co_u32_e32 v246, vcc, 0x8000, v246
	s_nop 1
	v_addc_co_u32_e32 v247, vcc, 0, v247, vcc
	v_cvt_pk_bf16_f32 v44, v44, v45
	v_cvt_pk_bf16_f32 v45, v46, v47
	v_cvt_pk_bf16_f32 v46, v40, v41
	v_cvt_pk_bf16_f32 v47, v42, v43
	v_cvt_pk_bf16_f32 v36, v36, v37
	v_cvt_pk_bf16_f32 v37, v38, v39
	v_cvt_pk_bf16_f32 v38, v32, v33
	v_cvt_pk_bf16_f32 v39, v34, v35
	s_nop 1
	v_permlane16_swap_b32_e32 v44, v46
	v_permlane16_swap_b32_e32 v45, v47
	v_permlane16_swap_b32_e32 v36, v38
	v_permlane16_swap_b32_e32 v37, v39
	global_store_dwordx4 v[246:247], v[44:47], off
	global_store_dwordx4 v[246:247], v[36:39], off offset:64
	v_add_co_u32_e32 v246, vcc, 0x8000, v246
	s_nop 1
	v_addc_co_u32_e32 v247, vcc, 0, v247, vcc
	v_cvt_pk_bf16_f32 v28, v28, v29
	v_cvt_pk_bf16_f32 v29, v30, v31
	v_cvt_pk_bf16_f32 v30, v24, v25
	v_cvt_pk_bf16_f32 v31, v26, v27
	v_cvt_pk_bf16_f32 v20, v20, v21
	v_cvt_pk_bf16_f32 v21, v22, v23
	v_cvt_pk_bf16_f32 v22, v16, v17
	v_cvt_pk_bf16_f32 v23, v18, v19
	s_nop 1
	v_permlane16_swap_b32_e32 v28, v30
	v_permlane16_swap_b32_e32 v29, v31
	v_permlane16_swap_b32_e32 v20, v22
	v_permlane16_swap_b32_e32 v21, v23
	global_store_dwordx4 v[246:247], v[28:31], off
	global_store_dwordx4 v[246:247], v[20:23], off offset:64
	v_add_co_u32_e32 v246, vcc, 0x8000, v246
	s_nop 1
	v_addc_co_u32_e32 v247, vcc, 0, v247, vcc
	v_cvt_pk_bf16_f32 v12, v12, v13
	v_cvt_pk_bf16_f32 v13, v14, v15
	v_cvt_pk_bf16_f32 v14, v8, v9
	v_cvt_pk_bf16_f32 v15, v10, v11
	v_cvt_pk_bf16_f32 v4, v4, v5
	v_cvt_pk_bf16_f32 v5, v6, v7
	v_cvt_pk_bf16_f32 v6, v0, v1
	v_cvt_pk_bf16_f32 v7, v2, v3
	s_nop 1
	v_permlane16_swap_b32_e32 v12, v14
	v_permlane16_swap_b32_e32 v13, v15
	v_permlane16_swap_b32_e32 v4, v6
	v_permlane16_swap_b32_e32 v5, v7
	global_store_dwordx4 v[246:247], v[12:15], off
	global_store_dwordx4 v[246:247], v[4:7], off offset:64
	s_andn2_b64 vcc, exec, s[30:31]
	s_cbranch_vccz .LBB0_271

.LBB0_644:
	v_readfirstlane_b32 s25, v166
	s_mul_hi_i32 s1, s30, 0x460000
	s_mul_i32 s0, s30, 0x460000
	s_and_b32 s38, s25, 0xc0
	s_or_b32 s29, s38, s24
	s_add_u32 s0, s18, s0
	s_addc_u32 s1, s19, s1
	s_ashr_i32 s31, s30, 31
	s_lshl_b64 s[36:37], s[30:31], 14
	s_add_u32 s64, s44, s36
	s_addc_u32 s65, s45, s37
	v_and_b32_e32 v248, 15, v166
	v_lshrrev_b32_e32 v249, 1, v166
	v_and_b32_e32 v249, 0x80, v249
	v_or_b32_e32 v248, v248, v249
	v_and_b32_e32 v249, 16, v166
	v_lshrrev_b32_e32 v250, 2, v166
	v_and_b32_e32 v250, 8, v250
	v_or_b32_e32 v249, v249, v250
	v_mul_u32_u24_e32 v250, 0x2300, v248
	v_add3_u32 v250, v250, v249, s29
	v_mov_b32_e32 v251, 0
	v_lshl_add_u64 v[246:247], v[250:251], 1, s[0:1]
	s_mov_b32 s26, 1.0
	s_cmpk_lt_u32 s29, 0x900
	s_cbranch_scc0 .Le1_b
	s_cmpk_ge_u32 s29, 0x600
	s_cselect_b32 s27, 0x600, 0
	s_sub_u32 s36, s29, s27
	s_cmpk_ge_u32 s36, 0x300
	s_cselect_b32 s27, 0x300, 0
	s_sub_u32 s36, s36, s27
	s_cmpk_lt_u32 s36, 0x100
	s_cselect_b32 s26, 0x3e38aa3b, s26
	s_cmpk_lt_u32 s36, 0x200
	s_cbranch_scc1 .Le1_rot
	s_branch .Le1_plain
.Le1_b:
	s_cmpk_lt_u32 s29, 0xf00
	s_cbranch_scc0 .Le1_c
	s_sub_u32 s36, s29, 0x900
	s_cmpk_lt_u32 s36, 0x200
	s_cselect_b32 s26, 0x3e38aa3b, s26
	s_cmpk_lt_u32 s36, 0x400
	s_cbranch_scc1 .Le1_rot
	s_branch .Le1_plain

.LBB0_900:
	s_add_i32 s0, s36, 63
	v_cmp_ge_i32_e32 vcc, s0, v46
	v_cmp_le_i32_e64 s[0:1], s36, v49
	s_and_b64 s[66:67], vcc, s[0:1]
	s_and_saveexec_b64 s[0:1], s[66:67]
	s_cbranch_execz .LBB0_897
	ds_read_b128 v[34:37], v53
	ds_read_b128 v[60:63], v53 offset:2304
	ds_read_b128 v[70:73], v53 offset:4608
	ds_read_b128 v[78:81], v53 offset:6912
	ds_read_b128 v[56:59], v53 offset:64
	ds_read_b128 v[66:69], v53 offset:2368
	ds_read_b128 v[74:77], v53 offset:4672
	ds_read_b128 v[82:85], v53 offset:6976
	s_waitcnt lgkmcnt(7)
	v_mfma_f32_16x16x32_bf16 v[34:37], v[34:37], v[4:7], 0
	s_waitcnt lgkmcnt(6)
	v_mfma_f32_16x16x32_bf16 v[60:63], v[60:63], v[4:7], 0
	s_waitcnt lgkmcnt(5)
	v_mfma_f32_16x16x32_bf16 v[70:73], v[70:73], v[4:7], 0
	s_waitcnt lgkmcnt(4)
	v_mfma_f32_16x16x32_bf16 v[78:81], v[78:81], v[4:7], 0
	s_waitcnt lgkmcnt(3)
	v_mfma_f32_16x16x32_bf16 v[34:37], v[56:59], v[8:11], v[34:37]
	s_waitcnt lgkmcnt(2)
	v_mfma_f32_16x16x32_bf16 v[56:59], v[66:69], v[8:11], v[60:63]
	s_waitcnt lgkmcnt(1)
	v_mfma_f32_16x16x32_bf16 v[60:63], v[74:77], v[8:11], v[70:73]
	s_waitcnt lgkmcnt(0)
	v_mfma_f32_16x16x32_bf16 v[66:69], v[82:85], v[8:11], v[78:81]
	v_add_u32_e32 v38, s37, v50
	v_add_u32_e32 v39, 0x80, v38
	v_cmp_gt_u32_e32 vcc, s22, v39
	v_add_u32_e32 v39, s36, v51
	v_add_u32_e32 v39, 0xffffff80, v39
	s_movk_i32 s61, 0xff7e
	v_cndmask_b32_e32 v34, v185, v34, vcc
	v_cmp_lt_u32_e32 vcc, s61, v39
	v_add_u32_e32 v39, 0x7e, v38
	v_add_u32_e32 v55, 0x6f, v38
	v_cndmask_b32_e32 v35, v185, v35, vcc
	v_cmp_gt_u32_e32 vcc, s22, v39
	v_add_u32_e32 v39, 0x7d, v38
	v_add_u32_e32 v64, 0x4e, v38
	v_cndmask_b32_e32 v36, v185, v36, vcc
	v_cmp_gt_u32_e32 vcc, s22, v39
	v_add_u32_e32 v39, 0x70, v38
	ds_read_b64_tr_b16 v[70:71], v54 offset:14400
	v_cndmask_b32_e32 v37, v185, v37, vcc
	v_cmp_gt_u32_e32 vcc, s22, v39
	ds_read_b64_tr_b16 v[72:73], v54 offset:16960
	ds_read_b64_tr_b16 v[74:75], v54 offset:9312
	v_cndmask_b32_e32 v39, v185, v56, vcc
	v_cmp_gt_u32_e32 vcc, s22, v55
	v_add_u32_e32 v56, 0x6e, v38
	ds_read_b64_tr_b16 v[76:77], v54 offset:11872
	v_cndmask_b32_e32 v55, v185, v57, vcc
	v_cmp_gt_u32_e32 vcc, s22, v56
	v_add_u32_e32 v57, 0x6d, v38
	s_nop 0
	v_cndmask_b32_e32 v56, v185, v58, vcc
	v_cmp_gt_u32_e32 vcc, s22, v57
	v_add_u32_e32 v58, 0x60, v38
	s_nop 0
	v_cndmask_b32_e32 v57, v185, v59, vcc
	v_cmp_gt_u32_e32 vcc, s22, v58
	v_add_u32_e32 v59, 0x5f, v38
	s_nop 0
	v_cndmask_b32_e32 v58, v185, v60, vcc
	v_cmp_gt_u32_e32 vcc, s22, v59
	v_add_u32_e32 v60, 0x5e, v38
	s_nop 0
	v_cndmask_b32_e32 v59, v185, v61, vcc
	v_cmp_gt_u32_e32 vcc, s22, v60
	v_add_u32_e32 v61, 0x5d, v38
	s_nop 0
	v_cndmask_b32_e32 v60, v185, v62, vcc
	v_cmp_gt_u32_e32 vcc, s22, v61
	v_add_u32_e32 v62, 0x50, v38
	s_nop 0
	v_cndmask_b32_e32 v61, v185, v63, vcc
	v_cmp_gt_u32_e32 vcc, s22, v62
	v_add_u32_e32 v63, 0x4f, v38
	v_add_u32_e32 v38, 0x4d, v38
	v_cndmask_b32_e32 v62, v185, v66, vcc
	v_cmp_gt_u32_e32 vcc, s22, v63
	s_nop 1
	v_cndmask_b32_e32 v63, v185, v67, vcc
	v_cmp_gt_u32_e32 vcc, s22, v64
	v_max3_f32 v64, v34, s33, v35
	v_max3_f32 v64, v64, v36, v37
	v_cndmask_b32_e32 v66, v185, v68, vcc
	v_cmp_gt_u32_e32 vcc, s22, v38
	v_max3_f32 v64, v64, v39, v55
	v_mbcnt_hi_u32_b32 v67, -1, v167
	v_cndmask_b32_e32 v38, v185, v69, vcc
	v_max3_f32 v64, v64, v56, v57
	v_and_b32_e32 v69, 64, v67
	v_max3_f32 v64, v64, v58, v59
	v_xor_b32_e32 v68, 16, v67
	v_add_u32_e32 v69, 64, v69
	v_max3_f32 v64, v64, v60, v61
	v_cmp_lt_i32_e32 vcc, v68, v69
	v_max3_f32 v64, v64, v62, v63
	v_max3_f32 v64, v64, v66, v38
	v_cndmask_b32_e32 v68, v67, v68, vcc
	v_lshlrev_b32_e32 v68, 2, v68
	ds_bpermute_b32 v68, v68, v64
	s_waitcnt lgkmcnt(0)
	v_max_f32_e32 v68, v68, v68
	v_max_f32_e32 v64, v64, v68
	v_xor_b32_e32 v68, 32, v67
	v_cmp_lt_i32_e32 vcc, v68, v69
	s_nop 1
	v_cndmask_b32_e32 v67, v67, v68, vcc
	v_lshlrev_b32_e32 v67, 2, v67
	ds_bpermute_b32 v67, v67, v64
	ds_read_b64_tr_b16 v[68:69], v54 offset:11840
	s_waitcnt lgkmcnt(1)
	v_max3_f32 v78, v32, v64, v67
	v_cmp_neq_f32_e32 vcc, s33, v78
	s_nop 1
	v_cndmask_b32_e32 v67, 0, v78, vcc
	v_sub_f32_e32 v32, v32, v67
	v_exp_f32_e32 v64, v32
	v_sub_f32_e32 v32, v34, v67
	v_sub_f32_e32 v34, v35, v67
	v_exp_f32_e32 v32, v32
	v_sub_f32_e32 v35, v36, v67
	v_exp_f32_e32 v34, v34
	v_sub_f32_e32 v36, v37, v67
	v_exp_f32_e32 v35, v35
	v_sub_f32_e32 v39, v39, v67
	v_exp_f32_e32 v37, v36
	v_sub_f32_e32 v55, v55, v67
	v_add_f32_e32 v36, 0, v32
	v_exp_f32_e32 v39, v39
	v_sub_f32_e32 v56, v56, v67
	v_add_f32_e32 v36, v34, v36
	v_exp_f32_e32 v55, v55
	v_sub_f32_e32 v57, v57, v67
	v_add_f32_e32 v36, v35, v36
	v_exp_f32_e32 v56, v56
	v_sub_f32_e32 v58, v58, v67
	v_add_f32_e32 v36, v37, v36
	v_exp_f32_e32 v57, v57
	v_sub_f32_e32 v59, v59, v67
	v_add_f32_e32 v36, v39, v36
	v_exp_f32_e32 v58, v58
	v_sub_f32_e32 v60, v60, v67
	v_add_f32_e32 v36, v55, v36
	v_exp_f32_e32 v59, v59
	v_sub_f32_e32 v61, v61, v67
	v_add_f32_e32 v36, v56, v36
	v_exp_f32_e32 v60, v60
	v_sub_f32_e32 v62, v62, v67
	v_add_f32_e32 v36, v57, v36
	v_exp_f32_e32 v61, v61
	v_sub_f32_e32 v63, v63, v67
	v_add_f32_e32 v36, v58, v36
	v_exp_f32_e32 v62, v62
	v_sub_f32_e32 v66, v66, v67
	v_add_f32_e32 v36, v59, v36
	v_exp_f32_e32 v63, v63
	v_sub_f32_e32 v38, v38, v67
	v_add_f32_e32 v36, v60, v36
	v_exp_f32_e32 v66, v66
	v_add_f32_e32 v36, v61, v36
	v_exp_f32_e32 v67, v38
	v_add_f32_e32 v36, v62, v36
	v_add_f32_e32 v36, v63, v36
	v_add_f32_e32 v36, v66, v36
	v_add_f32_e32 v79, v67, v36
	v_cvt_pk_bf16_f32 v36, v32, v34
	v_cvt_pk_bf16_f32 v38, v39, v55
	v_cvt_pk_bf16_f32 v39, v56, v57
	v_cvt_pk_bf16_f32 v32, v58, v59
	ds_read_b64_tr_b16 v[56:57], v54 offset:9248
	ds_read_b64_tr_b16 v[58:59], v54 offset:11808
	v_fmac_f32_e32 v79, v33, v64
	v_cvt_pk_bf16_f32 v33, v60, v61
	v_cvt_pk_bf16_f32 v34, v62, v63
	ds_read_b64_tr_b16 v[60:61], v54 offset:14368
	ds_read_b64_tr_b16 v[62:63], v54 offset:16928
	v_cvt_pk_bf16_f32 v37, v35, v37
	v_pk_mul_f32 v[2:3], v[2:3], v[64:65] op_sel_hi:[1,0]
	v_pk_mul_f32 v[0:1], v[0:1], v[64:65] op_sel_hi:[1,0]
	v_cvt_pk_bf16_f32 v35, v66, v67
	v_pk_mul_f32 v[26:27], v[26:27], v[64:65] op_sel_hi:[1,0]
	s_waitcnt lgkmcnt(2)
	v_mfma_f32_16x16x32_bf16 v[0:3], v[56:59], v[36:39], v[0:3]
	ds_read_b64_tr_b16 v[58:59], v54 offset:11776
	ds_read_b64_tr_b16 v[56:57], v54 offset:9216
	v_pk_mul_f32 v[24:25], v[24:25], v[64:65] op_sel_hi:[1,0]
	s_waitcnt lgkmcnt(2)
	v_mfma_f32_16x16x32_bf16 v[0:3], v[60:63], v[32:35], v[0:3]
	ds_read_b64_tr_b16 v[60:61], v54 offset:14336
	ds_read_b64_tr_b16 v[62:63], v54 offset:16896
	ds_read_b64_tr_b16 v[66:67], v54 offset:9280
	s_waitcnt lgkmcnt(3)
	v_mfma_f32_16x16x32_bf16 v[24:27], v[56:59], v[36:39], v[24:27]
	ds_read_b64_tr_b16 v[56:57], v54 offset:14432
	ds_read_b64_tr_b16 v[58:59], v54 offset:16992
	v_pk_mul_f32 v[30:31], v[30:31], v[64:65] op_sel_hi:[1,0]
	s_waitcnt lgkmcnt(3)
	v_mfma_f32_16x16x32_bf16 v[24:27], v[60:63], v[32:35], v[24:27]
	v_mul_f32_e64 v28, v28, v64
	v_mul_f32_e64 v29, v29, v64
	v_pk_mul_f32 v[22:23], v[22:23], v[64:65] op_sel_hi:[1,0]
	v_pk_mul_f32 v[20:21], v[20:21], v[64:65] op_sel_hi:[1,0]
	s_waitcnt lgkmcnt(2)
	v_mfma_f32_16x16x32_bf16 v[28:31], v[66:69], v[36:39], v[28:31]
	v_mfma_f32_16x16x32_bf16 v[20:23], v[74:77], v[36:39], v[20:23]
	v_mfma_f32_16x16x32_bf16 v[28:31], v[70:73], v[32:35], v[28:31]
	s_waitcnt lgkmcnt(0)
	v_mfma_f32_16x16x32_bf16 v[20:23], v[56:59], v[32:35], v[20:23]
	v_mov_b32_e32 v33, v79
	v_mov_b32_e32 v32, v78
	s_branch .LBB0_897
.LBB0_902:
	v_mbcnt_hi_u32_b32 v4, -1, v167
	v_and_b32_e32 v6, 64, v4
	v_xor_b32_e32 v5, 16, v4
	v_add_u32_e32 v6, 64, v6
	v_cmp_lt_i32_e32 vcc, v5, v6
	v_xor_b32_e32 v7, 32, v4
	s_movk_i32 s2, 0x600
	v_cndmask_b32_e32 v5, v4, v5, vcc
	v_lshlrev_b32_e32 v5, 2, v5
	ds_bpermute_b32 v5, v5, v33
	v_cmp_lt_i32_e32 vcc, v7, v6
	s_lshl_b32 s84, s27, 9
	v_lshlrev_b32_e32 v64, 1, v45
	v_cndmask_b32_e32 v4, v4, v7, vcc
	s_waitcnt lgkmcnt(0)
	v_add_f32_e32 v5, v33, v5
	v_lshlrev_b32_e32 v4, 2, v4
	ds_bpermute_b32 v4, v4, v5
	s_waitcnt lgkmcnt(0)
	v_add_f32_e32 v4, v5, v4
	v_div_scale_f32 v5, s[0:1], v4, v4, 1.0
	v_rcp_f32_e32 v6, v5
	v_readlane_b32 s0, v243, 51
	v_readlane_b32 s1, v243, 52
	v_fma_f32 v7, -v5, v6, 1.0
	v_fmac_f32_e32 v6, v7, v6
	v_div_scale_f32 v7, vcc, 1.0, v4, 1.0
	v_mul_f32_e32 v8, v7, v6
	v_fma_f32 v9, -v5, v8, v7
	v_fmac_f32_e32 v8, v9, v6
	v_fma_f32 v5, -v5, v8, v7
	v_div_fmas_f32 v5, v5, v6, v8
	v_mov_b64_e32 v[8:9], s[0:1]
	v_mad_u64_u32 v[8:9], s[0:1], v40, s2, v[8:9]
	v_mad_i32_i24 v9, v41, s2, v9
	v_div_fixup_f32 v6, v5, v4, 1.0
	v_lshl_add_u64 v[8:9], v[8:9], 0, s[84:85]
	s_lshl_b32 s84, s30, 1
	v_lshl_add_u64 v[8:9], v[8:9], 0, s[84:85]
	v_pk_mul_f32 v[0:1], v[0:1], v[6:7] op_sel_hi:[1,0]
	v_pk_mul_f32 v[2:3], v[2:3], v[6:7] op_sel_hi:[1,0]
	v_lshl_add_u64 v[8:9], v[8:9], 0, v[64:65]
	v_cvt_pk_bf16_f32 v0, v0, v1
	v_cvt_pk_bf16_f32 v1, v2, v3
	global_store_dwordx2 v[8:9], v[0:1], off offset:32
	v_pk_mul_f32 v[0:1], v[28:29], v[6:7] op_sel_hi:[1,0]
	v_pk_mul_f32 v[2:3], v[30:31], v[6:7] op_sel_hi:[1,0]
	v_cvt_pk_bf16_f32 v0, v0, v1
	v_cvt_pk_bf16_f32 v1, v2, v3
	v_pk_mul_f32 v[10:11], v[24:25], v[6:7] op_sel_hi:[1,0]
	s_waitcnt vmcnt(2)
	v_pk_mul_f32 v[12:13], v[26:27], v[6:7] op_sel_hi:[1,0]
	global_store_dwordx2 v[8:9], v[0:1], off offset:64
	v_pk_mul_f32 v[0:1], v[20:21], v[6:7] op_sel_hi:[1,0]
	v_pk_mul_f32 v[2:3], v[22:23], v[6:7] op_sel_hi:[1,0]
	v_cvt_pk_bf16_f32 v10, v10, v11
	v_cvt_pk_bf16_f32 v11, v12, v13
	v_cvt_pk_bf16_f32 v0, v0, v1
	v_cvt_pk_bf16_f32 v1, v2, v3
	v_cmp_eq_u32_e32 vcc, 0, v44
	global_store_dwordx2 v[8:9], v[10:11], off
	global_store_dwordx2 v[8:9], v[0:1], off offset:96
	s_and_saveexec_b64 s[0:1], vcc
	s_xor_b64 s[0:1], exec, s[0:1]
	s_cbranch_execz .LBB0_904
	s_mov_b32 s2, 0x800000
	v_cmp_gt_f32_e32 vcc, s2, v4
	s_mov_b32 s2, 0x3f317217
	v_readlane_b32 s28, v243, 53
	v_cndmask_b32_e64 v0, 0, 32, vcc
	v_ldexp_f32 v0, v4, v0
	v_log_f32_e32 v0, v0
	v_cndmask_b32_e32 v1, 0, v179, vcc
	v_readlane_b32 s29, v243, 54
	s_lshl_b32 s84, s27, 4
	v_mul_f32_e32 v2, 0x3f317217, v0
	v_fma_f32 v2, v0, s2, -v2
	v_fmac_f32_e32 v2, 0x3377d1cf, v0
	s_mov_b32 s2, 0x7f800000
	v_fmac_f32_e32 v2, 0x3f317217, v0
	v_cmp_lt_f32_e64 vcc, |v0|, s2
	s_nop 1
	v_cndmask_b32_e32 v0, v0, v2, vcc
	v_sub_f32_e32 v0, v0, v1
	v_fmamk_f32 v2, v32, 0x3f317218, v0
	v_mad_u64_u32 v[0:1], s[28:29], v40, 48, s[28:29]
	v_mad_i32_i24 v1, v41, 48, v1
	v_lshl_add_u64 v[0:1], v[0:1], 0, s[84:85]
	s_lshl_b32 s84, s26, 2
	v_lshl_add_u64 v[0:1], v[0:1], 0, s[84:85]
	global_store_dword v[0:1], v2, off

.LBB0_908:
	s_or_b64 exec, exec, s[26:27]
	v_max3_f32 v136, v126, s33, v127
	v_max3_f32 v136, v136, v128, v129
	v_max3_f32 v136, v136, v122, v123
	v_mbcnt_hi_u32_b32 v137, -1, v167
	v_max3_f32 v136, v136, v124, v125
	v_and_b32_e32 v143, 64, v137
	v_max3_f32 v136, v136, v52, v53
	v_xor_b32_e32 v142, 16, v137
	v_add_u32_e32 v143, 64, v143
	v_max3_f32 v136, v136, v54, v55
	v_cmp_lt_i32_e32 vcc, v142, v143
	v_max3_f32 v136, v136, v48, v49
	v_max3_f32 v136, v136, v50, v51
	v_cndmask_b32_e32 v142, v137, v142, vcc
	v_lshlrev_b32_e32 v144, 2, v142
	ds_bpermute_b32 v142, v144, v136
	s_waitcnt lgkmcnt(0)
	v_max_f32_e32 v142, v142, v142
	v_max_f32_e32 v136, v136, v142
	v_xor_b32_e32 v142, 32, v137
	v_cmp_lt_i32_e32 vcc, v142, v143
	s_nop 1
	v_cndmask_b32_e32 v137, v137, v142, vcc
	v_lshlrev_b32_e32 v143, 2, v137
	ds_bpermute_b32 v137, v143, v136
	s_waitcnt lgkmcnt(0)
	v_max3_f32 v142, v198, v136, v137
	v_cmp_neq_f32_e32 vcc, s33, v142
	s_nop 1
	v_cndmask_b32_e32 v136, 0, v142, vcc
	v_sub_f32_e32 v48, v48, v136
	v_exp_f32_e32 v209, v48
	v_sub_f32_e32 v48, v49, v136
	v_exp_f32_e32 v211, v48
	v_sub_f32_e32 v48, v50, v136
	v_exp_f32_e32 v213, v48
	v_sub_f32_e32 v48, v51, v136
	v_sub_f32_e32 v52, v52, v136
	v_exp_f32_e32 v215, v48
	v_max3_f32 v48, v118, s33, v119
	v_exp_f32_e32 v201, v52
	v_sub_f32_e32 v52, v53, v136
	v_max3_f32 v48, v48, v120, v121
	v_max3_f32 v48, v48, v114, v115
	v_exp_f32_e32 v203, v52
	v_sub_f32_e32 v52, v54, v136
	v_max3_f32 v48, v48, v116, v117
	v_max3_f32 v48, v48, v60, v61
	v_exp_f32_e32 v205, v52
	v_sub_f32_e32 v52, v55, v136
	v_max3_f32 v48, v48, v62, v63
	v_sub_f32_e32 v122, v122, v136
	v_max3_f32 v48, v48, v56, v57
	v_exp_f32_e32 v207, v52
	v_max3_f32 v52, v48, v58, v59
	v_exp_f32_e32 v163, v122
	v_sub_f32_e32 v122, v123, v136
	ds_bpermute_b32 v53, v144, v52
	v_exp_f32_e32 v165, v122
	v_sub_f32_e32 v122, v124, v136
	v_exp_f32_e32 v199, v122
	v_sub_f32_e32 v122, v125, v136
	s_waitcnt lgkmcnt(0)
	v_max_f32_e32 v53, v53, v53
	v_exp_f32_e32 v125, v122
	v_max_f32_e32 v122, v52, v53
	ds_bpermute_b32 v123, v143, v122
	v_sub_f32_e32 v126, v126, v136
	v_exp_f32_e32 v145, v126
	v_sub_f32_e32 v126, v127, v136
	s_waitcnt lgkmcnt(0)
	v_max3_f32 v122, v162, v122, v123
	v_cmp_neq_f32_e32 vcc, s33, v122
	v_exp_f32_e32 v127, v126
	s_nop 0
	v_cndmask_b32_e32 v123, 0, v122, vcc
	v_sub_f32_e32 v126, v128, v136
	v_sub_f32_e32 v118, v118, v123
	v_sub_f32_e32 v114, v114, v123
	v_exp_f32_e32 v153, v126
	v_sub_f32_e32 v126, v129, v136
	v_exp_f32_e32 v144, v118
	v_sub_f32_e32 v118, v119, v123
	v_sub_f32_e32 v124, v162, v123
	v_exp_f32_e32 v162, v114
	v_sub_f32_e32 v114, v115, v123
	v_exp_f32_e32 v129, v126
	v_exp_f32_e32 v126, v118
	v_sub_f32_e32 v118, v120, v123
	v_exp_f32_e32 v164, v114
	v_sub_f32_e32 v114, v116, v123
	v_exp_f32_e32 v152, v118
	v_sub_f32_e32 v118, v121, v123
	v_sub_f32_e32 v137, v198, v136
	v_exp_f32_e32 v198, v114
	v_sub_f32_e32 v114, v117, v123
	v_exp_f32_e32 v128, v118
	v_sub_f32_e32 v60, v60, v123
	v_exp_f32_e32 v136, v124
	v_exp_f32_e32 v124, v114
	v_pk_add_f32 v[114:115], v[144:145], 0 op_sel_hi:[1,0]
	v_exp_f32_e32 v200, v60
	v_pk_add_f32 v[114:115], v[126:127], v[114:115]
	v_sub_f32_e32 v60, v61, v123
	v_sub_f32_e32 v56, v56, v123
	v_pk_add_f32 v[114:115], v[152:153], v[114:115]
	v_pk_add_f32 v[114:115], v[128:129], v[114:115]
	v_exp_f32_e32 v202, v60
	v_sub_f32_e32 v60, v62, v123
	v_exp_f32_e32 v208, v56
	v_sub_f32_e32 v56, v57, v123
	v_pk_add_f32 v[114:115], v[162:163], v[114:115]
	v_pk_add_f32 v[114:115], v[164:165], v[114:115]
	v_exp_f32_e32 v204, v60
	v_sub_f32_e32 v60, v63, v123
	v_exp_f32_e32 v210, v56
	v_sub_f32_e32 v56, v58, v123
	v_pk_add_f32 v[114:115], v[198:199], v[114:115]
	v_exp_f32_e32 v137, v137
	v_pk_add_f32 v[114:115], v[124:125], v[114:115]
	v_exp_f32_e32 v206, v60
	v_exp_f32_e32 v212, v56
	v_sub_f32_e32 v56, v59, v123
	v_pk_add_f32 v[114:115], v[200:201], v[114:115]
	v_exp_f32_e32 v214, v56
	v_pk_add_f32 v[56:57], v[202:203], v[114:115]
	v_mov_b32_e32 v118, v137
	v_pk_add_f32 v[56:57], v[204:205], v[56:57]
	v_add_u32_e32 v123, v158, v159
	v_pk_add_f32 v[56:57], v[206:207], v[56:57]
	v_cvt_pk_bf16_f32 v50, v163, v165
	v_pk_add_f32 v[56:57], v[208:209], v[56:57]
	v_cvt_pk_bf16_f32 v62, v162, v164
	v_pk_mul_f32 v[116:117], v[2:3], v[118:119] op_sel_hi:[1,0]
	v_pk_mul_f32 v[114:115], v[0:1], v[118:119] op_sel_hi:[1,0]
	v_pk_mul_f32 v[2:3], v[96:97], v[136:137] op_sel_hi:[1,0]
	v_pk_mul_f32 v[0:1], v[94:95], v[136:137] op_sel_hi:[1,0]
	ds_read_b64_tr_b16 v[94:95], v123 offset:18464
	ds_read_b64_tr_b16 v[96:97], v123 offset:23072
	ds_read_b64_tr_b16 v[164:165], v123 offset:23040
	ds_read_b64_tr_b16 v[162:163], v123 offset:18432
	v_pk_add_f32 v[56:57], v[210:211], v[56:57]
	v_cvt_pk_bf16_f32 v51, v199, v125
	v_pk_add_f32 v[56:57], v[212:213], v[56:57]
	v_cvt_pk_bf16_f32 v52, v201, v203
	v_pk_add_f32 v[56:57], v[214:215], v[56:57]
	v_cvt_pk_bf16_f32 v63, v198, v124
	v_pk_fma_f32 v[148:149], v[148:149], v[136:137], v[56:57]
	v_cvt_pk_bf16_f32 v56, v200, v202
	ds_read_b64_tr_b16 v[198:199], v123 offset:27648
	ds_read_b64_tr_b16 v[200:201], v123 offset:32256
	v_cvt_pk_bf16_f32 v48, v145, v127
	v_cvt_pk_bf16_f32 v49, v153, v129
	v_cvt_pk_bf16_f32 v60, v144, v126
	v_cvt_pk_bf16_f32 v61, v152, v128
	v_pk_mul_f32 v[6:7], v[6:7], v[118:119] op_sel_hi:[1,0]
	v_pk_mul_f32 v[4:5], v[4:5], v[118:119] op_sel_hi:[1,0]
	v_pk_mul_f32 v[68:69], v[68:69], v[136:137] op_sel_hi:[1,0]
	v_pk_mul_f32 v[66:67], v[66:67], v[136:137] op_sel_hi:[1,0]
	s_waitcnt lgkmcnt(4)
	v_mfma_f32_16x16x32_bf16 v[4:7], v[94:97], v[48:51], v[4:7]
	v_cvt_pk_bf16_f32 v53, v205, v207
	v_cvt_pk_bf16_f32 v54, v209, v211
	v_cvt_pk_bf16_f32 v55, v213, v215
	v_mfma_f32_16x16x32_bf16 v[66:69], v[94:97], v[60:63], v[66:69]
	v_cvt_pk_bf16_f32 v57, v204, v206
	v_cvt_pk_bf16_f32 v58, v208, v210
	v_cvt_pk_bf16_f32 v59, v212, v214
	s_waitcnt lgkmcnt(2)
	v_mfma_f32_16x16x32_bf16 v[94:97], v[162:165], v[48:51], v[114:117]
	v_mul_f32_e64 v10, v10, v118
	v_mul_f32_e64 v11, v11, v118
	v_pk_mul_f32 v[8:9], v[8:9], v[118:119] op_sel_hi:[1,0]
	v_pk_mul_f32 v[14:15], v[14:15], v[118:119] op_sel_hi:[1,0]
	v_mfma_f32_16x16x32_bf16 v[114:117], v[162:165], v[60:63], v[0:3]
	ds_read_b64_tr_b16 v[162:163], v123 offset:18528
	v_pk_mul_f32 v[12:13], v[12:13], v[118:119] op_sel_hi:[1,0]
	v_pk_mul_f32 v[18:19], v[18:19], v[118:119] op_sel_hi:[1,0]
	s_waitcnt lgkmcnt(1)
	v_mfma_f32_16x16x32_bf16 v[0:3], v[198:201], v[52:55], v[94:97]
	v_mul_f32_e64 v16, v16, v118
	v_mul_f32_e64 v17, v17, v118
	v_pk_mul_f32 v[22:23], v[22:23], v[118:119] op_sel_hi:[1,0]
	v_pk_mul_f32 v[20:21], v[20:21], v[118:119] op_sel_hi:[1,0]
	v_mfma_f32_16x16x32_bf16 v[94:97], v[198:201], v[56:59], v[114:117]
	ds_read_b64_tr_b16 v[124:125], v123 offset:27680
	ds_read_b64_tr_b16 v[126:127], v123 offset:32288
	v_pk_mul_f32 v[26:27], v[26:27], v[118:119] op_sel_hi:[1,0]
	s_waitcnt lgkmcnt(0)
	v_mfma_f32_16x16x32_bf16 v[4:7], v[124:127], v[52:55], v[4:7]
	v_mul_f32_e64 v24, v24, v118
	v_mul_f32_e64 v25, v25, v118
	v_pk_mul_f32 v[30:31], v[30:31], v[118:119] op_sel_hi:[1,0]
	v_pk_mul_f32 v[28:29], v[28:29], v[118:119] op_sel_hi:[1,0]
	v_mfma_f32_16x16x32_bf16 v[66:69], v[124:127], v[56:59], v[66:69]
	ds_read_b64_tr_b16 v[118:119], v123 offset:18496
	ds_read_b64_tr_b16 v[120:121], v123 offset:23104
	ds_read_b64_tr_b16 v[124:125], v123 offset:27712
	ds_read_b64_tr_b16 v[126:127], v123 offset:32320
	ds_read_b64_tr_b16 v[164:165], v123 offset:23136
	ds_read_b64_tr_b16 v[202:203], v123 offset:27744
	ds_read_b64_tr_b16 v[204:205], v123 offset:32352
	v_pk_mul_f32 v[88:89], v[88:89], v[136:137] op_sel_hi:[1,0]
	v_pk_mul_f32 v[86:87], v[86:87], v[136:137] op_sel_hi:[1,0]
	v_pk_mul_f32 v[92:93], v[92:93], v[136:137] op_sel_hi:[1,0]
	v_pk_mul_f32 v[90:91], v[90:91], v[136:137] op_sel_hi:[1,0]
	v_pk_mul_f32 v[72:73], v[72:73], v[136:137] op_sel_hi:[1,0]
	v_pk_mul_f32 v[70:71], v[70:71], v[136:137] op_sel_hi:[1,0]
	v_pk_mul_f32 v[76:77], v[76:77], v[136:137] op_sel_hi:[1,0]
	v_pk_mul_f32 v[74:75], v[74:75], v[136:137] op_sel_hi:[1,0]
	v_pk_mul_f32 v[80:81], v[80:81], v[136:137] op_sel_hi:[1,0]
	v_pk_mul_f32 v[78:79], v[78:79], v[136:137] op_sel_hi:[1,0]
	v_pk_mul_f32 v[84:85], v[84:85], v[136:137] op_sel_hi:[1,0]
	v_pk_mul_f32 v[82:83], v[82:83], v[136:137] op_sel_hi:[1,0]
	s_waitcnt lgkmcnt(5)
	v_mfma_f32_16x16x32_bf16 v[8:11], v[118:121], v[48:51], v[8:11]
	ds_read_b64_tr_b16 v[116:117], v123 offset:23168
	ds_read_b64_tr_b16 v[198:199], v123 offset:27776
	ds_read_b64_tr_b16 v[200:201], v123 offset:32384
	ds_read_b64_tr_b16 v[114:115], v123 offset:18560
	ds_read_b64_tr_b16 v[206:207], v123 offset:18592
	ds_read_b64_tr_b16 v[208:209], v123 offset:23200
	ds_read_b64_tr_b16 v[210:211], v123 offset:27808
	ds_read_b64_tr_b16 v[212:213], v123 offset:32416
	v_mfma_f32_16x16x32_bf16 v[86:89], v[118:121], v[60:63], v[86:89]
	s_waitcnt lgkmcnt(10)
	v_mfma_f32_16x16x32_bf16 v[12:15], v[162:165], v[48:51], v[12:15]
	v_mfma_f32_16x16x32_bf16 v[90:93], v[162:165], v[60:63], v[90:93]
	v_mfma_f32_16x16x32_bf16 v[8:11], v[124:127], v[52:55], v[8:11]
	v_mfma_f32_16x16x32_bf16 v[86:89], v[124:127], v[56:59], v[86:89]
	s_waitcnt lgkmcnt(8)
	v_mfma_f32_16x16x32_bf16 v[12:15], v[202:205], v[52:55], v[12:15]
	v_mfma_f32_16x16x32_bf16 v[90:93], v[202:205], v[56:59], v[90:93]
	s_waitcnt lgkmcnt(4)
	v_mfma_f32_16x16x32_bf16 v[16:19], v[114:117], v[48:51], v[16:19]
	ds_read_b64_tr_b16 v[120:121], v123 offset:23232
	ds_read_b64_tr_b16 v[124:125], v123 offset:27840
	ds_read_b64_tr_b16 v[126:127], v123 offset:32448
	ds_read_b64_tr_b16 v[118:119], v123 offset:18624
	ds_read_b64_tr_b16 v[162:163], v123 offset:18656
	ds_read_b64_tr_b16 v[164:165], v123 offset:23264
	ds_read_b64_tr_b16 v[202:203], v123 offset:27872
	ds_read_b64_tr_b16 v[204:205], v123 offset:32480
	v_mfma_f32_16x16x32_bf16 v[70:73], v[114:117], v[60:63], v[70:73]
	s_waitcnt lgkmcnt(10)
	v_mfma_f32_16x16x32_bf16 v[20:23], v[206:209], v[48:51], v[20:23]
	v_mfma_f32_16x16x32_bf16 v[74:77], v[206:209], v[60:63], v[74:77]
	v_mfma_f32_16x16x32_bf16 v[16:19], v[198:201], v[52:55], v[16:19]
	v_mfma_f32_16x16x32_bf16 v[70:73], v[198:201], v[56:59], v[70:73]
	s_waitcnt lgkmcnt(8)
	v_mfma_f32_16x16x32_bf16 v[20:23], v[210:213], v[52:55], v[20:23]
	v_mfma_f32_16x16x32_bf16 v[74:77], v[210:213], v[56:59], v[74:77]
	s_waitcnt lgkmcnt(4)
	v_mfma_f32_16x16x32_bf16 v[24:27], v[118:121], v[48:51], v[24:27]
	v_mfma_f32_16x16x32_bf16 v[78:81], v[118:121], v[60:63], v[78:81]
	s_waitcnt lgkmcnt(2)
	v_mfma_f32_16x16x32_bf16 v[28:31], v[162:165], v[48:51], v[28:31]
	v_mfma_f32_16x16x32_bf16 v[48:51], v[162:165], v[60:63], v[82:85]
	v_mfma_f32_16x16x32_bf16 v[24:27], v[124:127], v[52:55], v[24:27]
	v_mfma_f32_16x16x32_bf16 v[78:81], v[124:127], v[56:59], v[78:81]
	s_waitcnt lgkmcnt(0)
	v_mfma_f32_16x16x32_bf16 v[28:31], v[202:205], v[52:55], v[28:31]
	v_mfma_f32_16x16x32_bf16 v[82:85], v[202:205], v[56:59], v[48:51]
	v_mov_b32_e32 v198, v142
	v_mov_b32_e32 v162, v122

.LBB0_916:
	s_or_b64 exec, exec, s[26:27]
	v_max3_f32 v64, v60, s33, v61
	v_max3_f32 v64, v64, v62, v63
	v_max3_f32 v64, v64, v56, v57
	v_mbcnt_hi_u32_b32 v163, -1, v167
	v_max3_f32 v64, v64, v58, v59
	v_and_b32_e32 v98, 64, v163
	v_max3_f32 v64, v64, v52, v53
	v_xor_b32_e32 v165, 16, v163
	v_add_u32_e32 v164, 64, v98
	v_max3_f32 v64, v64, v54, v55
	v_cmp_lt_i32_e32 vcc, v165, v164
	v_max3_f32 v64, v64, v48, v49
	v_max3_f32 v64, v64, v50, v51
	v_cndmask_b32_e32 v98, v163, v165, vcc
	v_lshlrev_b32_e32 v98, 2, v98
	ds_bpermute_b32 v99, v98, v64
	v_xor_b32_e32 v197, 32, v163
	v_cmp_lt_i32_e32 vcc, v197, v164
	s_waitcnt lgkmcnt(0)
	v_max_f32_e32 v99, v99, v99
	v_max_f32_e32 v64, v64, v99
	v_cndmask_b32_e32 v99, v163, v197, vcc
	v_lshlrev_b32_e32 v99, 2, v99
	ds_bpermute_b32 v100, v99, v64
	s_waitcnt lgkmcnt(0)
	v_max3_f32 v64, v198, v64, v100
	v_cmp_neq_f32_e32 vcc, s33, v64
	s_nop 1
	v_cndmask_b32_e32 v64, 0, v64, vcc
	v_sub_f32_e32 v48, v48, v64
	v_exp_f32_e32 v123, v48
	v_sub_f32_e32 v48, v49, v64
	v_exp_f32_e32 v49, v48
	v_sub_f32_e32 v48, v50, v64
	v_exp_f32_e32 v125, v48
	v_sub_f32_e32 v48, v51, v64
	v_exp_f32_e32 v51, v48
	v_max3_f32 v48, v44, s33, v45
	v_max3_f32 v48, v48, v46, v47
	v_max3_f32 v48, v48, v40, v41
	v_max3_f32 v48, v48, v42, v43
	v_max3_f32 v48, v48, v36, v37
	v_max3_f32 v48, v48, v38, v39
	v_max3_f32 v48, v48, v32, v33
	v_max3_f32 v48, v48, v34, v35
	ds_bpermute_b32 v50, v98, v48
	v_sub_f32_e32 v60, v60, v64
	v_sub_f32_e32 v56, v56, v64
	v_exp_f32_e32 v103, v60
	s_waitcnt lgkmcnt(0)
	v_max_f32_e32 v50, v50, v50
	v_max_f32_e32 v48, v48, v50
	ds_bpermute_b32 v50, v99, v48
	v_sub_f32_e32 v60, v61, v64
	v_exp_f32_e32 v115, v56
	s_waitcnt lgkmcnt(0)
	v_max3_f32 v48, v162, v48, v50
	v_cmp_neq_f32_e32 vcc, s33, v48
	v_sub_f32_e32 v56, v57, v64
	v_exp_f32_e32 v105, v60
	v_cndmask_b32_e32 v50, 0, v48, vcc
	v_sub_f32_e32 v44, v44, v50
	v_exp_f32_e32 v102, v44
	v_sub_f32_e32 v44, v45, v50
	v_sub_f32_e32 v60, v62, v64
	v_sub_f32_e32 v52, v52, v64
	v_exp_f32_e32 v104, v44
	v_sub_f32_e32 v44, v46, v50
	v_exp_f32_e32 v57, v56
	v_sub_f32_e32 v56, v58, v64
	v_sub_f32_e32 v40, v40, v50
	v_exp_f32_e32 v109, v60
	v_sub_f32_e32 v60, v63, v64
	v_exp_f32_e32 v119, v52
	v_sub_f32_e32 v52, v53, v64
	v_exp_f32_e32 v108, v44
	v_sub_f32_e32 v44, v47, v50
	v_exp_f32_e32 v117, v56
	v_sub_f32_e32 v56, v59, v64
	v_exp_f32_e32 v114, v40
	v_sub_f32_e32 v40, v41, v50
	v_sub_f32_e32 v32, v32, v50
	v_exp_f32_e32 v113, v60
	v_exp_f32_e32 v53, v52
	v_sub_f32_e32 v52, v54, v64
	v_exp_f32_e32 v112, v44
	v_sub_f32_e32 v42, v42, v50
	v_sub_f32_e32 v36, v36, v50
	v_exp_f32_e32 v59, v56
	v_sub_f32_e32 v48, v162, v50
	v_exp_f32_e32 v56, v40
	v_pk_add_f32 v[40:41], v[102:103], 0 op_sel_hi:[1,0]
	v_exp_f32_e32 v122, v32
	v_sub_f32_e32 v32, v33, v50
	v_exp_f32_e32 v121, v52
	v_sub_f32_e32 v52, v55, v64
	v_pk_add_f32 v[40:41], v[104:105], v[40:41]
	v_exp_f32_e32 v116, v42
	v_sub_f32_e32 v42, v43, v50
	v_exp_f32_e32 v118, v36
	v_sub_f32_e32 v36, v37, v50
	v_exp_f32_e32 v110, v48
	v_pk_add_f32 v[40:41], v[108:109], v[40:41]
	v_exp_f32_e32 v48, v32
	v_sub_f32_e32 v32, v34, v50
	v_exp_f32_e32 v55, v52
	v_pk_add_f32 v[40:41], v[112:113], v[40:41]
	v_exp_f32_e32 v58, v42
	v_exp_f32_e32 v52, v36
	v_sub_f32_e32 v36, v38, v50
	v_pk_add_f32 v[40:41], v[114:115], v[40:41]
	v_exp_f32_e32 v124, v32
	v_sub_f32_e32 v32, v35, v50
	v_pk_add_f32 v[40:41], v[56:57], v[40:41]
	v_exp_f32_e32 v120, v36
	v_sub_f32_e32 v36, v39, v50
	v_exp_f32_e32 v50, v32
	v_pk_add_f32 v[32:33], v[116:117], v[40:41]
	v_exp_f32_e32 v54, v36
	v_pk_add_f32 v[32:33], v[58:59], v[32:33]
	v_cvt_pk_bf16_f32 v61, v109, v113
	v_pk_add_f32 v[32:33], v[118:119], v[32:33]
	v_cvt_pk_bf16_f32 v109, v116, v58
	v_pk_add_f32 v[32:33], v[52:53], v[32:33]
	v_add_u32_e32 v58, v158, v159
	v_pk_add_f32 v[32:33], v[120:121], v[32:33]
	v_cvt_pk_bf16_f32 v60, v103, v105
	v_pk_add_f32 v[32:33], v[54:55], v[32:33]
	v_cvt_pk_bf16_f32 v98, v119, v53
	v_pk_add_f32 v[32:33], v[122:123], v[32:33]
	v_cvt_pk_bf16_f32 v101, v125, v51
	v_pk_add_f32 v[32:33], v[48:49], v[32:33]
	v_cvt_pk_bf16_f32 v106, v102, v104
	v_pk_add_f32 v[32:33], v[124:125], v[32:33]
	v_cvt_pk_bf16_f32 v102, v118, v52
	v_pk_add_f32 v[32:33], v[50:51], v[32:33]
	v_cvt_pk_bf16_f32 v105, v124, v50
	ds_read_b64_tr_b16 v[50:51], v58 offset:18464
	ds_read_b64_tr_b16 v[52:53], v58 offset:23072
	v_sub_f32_e32 v100, v198, v64
	v_exp_f32_e32 v111, v100
	v_cvt_pk_bf16_f32 v62, v115, v57
	v_cvt_pk_bf16_f32 v99, v121, v55
	v_cvt_pk_bf16_f32 v107, v108, v112
	v_cvt_pk_bf16_f32 v108, v114, v56
	v_cvt_pk_bf16_f32 v103, v120, v54
	ds_read_b64_tr_b16 v[112:113], v58 offset:27680
	ds_read_b64_tr_b16 v[114:115], v58 offset:32288
	ds_read_b64_tr_b16 v[120:121], v58 offset:23040
	ds_read_b64_tr_b16 v[118:119], v58 offset:18432
	v_cvt_pk_bf16_f32 v104, v122, v48
	v_mov_b32_e32 v48, v111
	v_cvt_pk_bf16_f32 v63, v117, v59
	v_pk_mul_f32 v[38:39], v[6:7], v[48:49] op_sel_hi:[1,0]
	v_pk_mul_f32 v[36:37], v[4:5], v[48:49] op_sel_hi:[1,0]
	v_pk_mul_f32 v[46:47], v[68:69], v[110:111] op_sel_hi:[1,0]
	v_pk_mul_f32 v[44:45], v[66:67], v[110:111] op_sel_hi:[1,0]
	ds_read_b64_tr_b16 v[134:135], v58 offset:27648
	ds_read_b64_tr_b16 v[136:137], v58 offset:32256
	s_waitcnt lgkmcnt(6)
	v_mfma_f32_16x16x32_bf16 v[36:39], v[50:53], v[60:63], v[36:39]
	v_cvt_pk_bf16_f32 v100, v123, v49
	v_pk_fma_f32 v[152:153], v[148:149], v[110:111], v[32:33]
	v_pk_mul_f32 v[42:43], v[2:3], v[48:49] op_sel_hi:[1,0]
	v_mfma_f32_16x16x32_bf16 v[44:47], v[50:53], v[106:109], v[44:47]
	v_mul_f32_e64 v40, v0, v48
	v_mul_f32_e64 v41, v1, v48
	v_pk_mul_f32 v[34:35], v[96:97], v[110:111] op_sel_hi:[1,0]
	v_pk_mul_f32 v[32:33], v[94:95], v[110:111] op_sel_hi:[1,0]
	s_waitcnt lgkmcnt(4)
	v_mfma_f32_16x16x32_bf16 v[36:39], v[112:115], v[98:101], v[36:39]
	ds_read_b64_tr_b16 v[210:211], v58 offset:27712
	ds_read_b64_tr_b16 v[212:213], v58 offset:32320
	ds_read_b64_tr_b16 v[214:215], v58 offset:18528
	v_mfma_f32_16x16x32_bf16 v[114:117], v[112:115], v[102:105], v[44:47]
	ds_read_b64_tr_b16 v[216:217], v58 offset:23136
	ds_read_b64_tr_b16 v[218:219], v58 offset:27744
	ds_read_b64_tr_b16 v[220:221], v58 offset:32352
	s_waitcnt lgkmcnt(8)
	v_mfma_f32_16x16x32_bf16 v[40:43], v[118:121], v[60:63], v[40:43]
	v_mul_f32_e64 v56, v10, v48
	v_mul_f32_e64 v57, v11, v48
	v_pk_mul_f32 v[54:55], v[8:9], v[48:49] op_sel_hi:[1,0]
	v_pk_mul_f32 v[124:125], v[88:89], v[110:111] op_sel_hi:[1,0]
	v_mfma_f32_16x16x32_bf16 v[44:47], v[118:121], v[106:109], v[32:35]
	v_mul_f32_e64 v122, v86, v110
	v_mul_f32_e64 v123, v87, v110
	v_pk_mul_f32 v[128:129], v[14:15], v[48:49] op_sel_hi:[1,0]
	v_pk_mul_f32 v[126:127], v[12:13], v[48:49] op_sel_hi:[1,0]
	s_waitcnt lgkmcnt(6)
	v_mfma_f32_16x16x32_bf16 v[118:121], v[134:137], v[102:105], v[44:47]
	v_mul_f32_e64 v132, v92, v110
	v_mul_f32_e64 v133, v93, v110
	v_pk_mul_f32 v[130:131], v[90:91], v[110:111] op_sel_hi:[1,0]
	v_pk_mul_f32 v[52:53], v[18:19], v[48:49] op_sel_hi:[1,0]
	v_mfma_f32_16x16x32_bf16 v[32:35], v[134:137], v[98:101], v[40:43]
	v_mul_f32_e64 v50, v16, v48
	v_mul_f32_e64 v51, v17, v48
	v_pk_mul_f32 v[140:141], v[72:73], v[110:111] op_sel_hi:[1,0]
	v_pk_mul_f32 v[138:139], v[70:71], v[110:111] op_sel_hi:[1,0]
	ds_read_b64_tr_b16 v[40:41], v58 offset:18496
	ds_read_b64_tr_b16 v[42:43], v58 offset:23104
	v_pk_mul_f32 v[144:145], v[22:23], v[48:49] op_sel_hi:[1,0]
	v_pk_mul_f32 v[142:143], v[20:21], v[48:49] op_sel_hi:[1,0]
	v_pk_mul_f32 v[160:161], v[76:77], v[110:111] op_sel_hi:[1,0]
	v_pk_mul_f32 v[158:159], v[74:75], v[110:111] op_sel_hi:[1,0]
	v_pk_mul_f32 v[200:201], v[26:27], v[48:49] op_sel_hi:[1,0]
	v_pk_mul_f32 v[198:199], v[24:25], v[48:49] op_sel_hi:[1,0]
	v_pk_mul_f32 v[204:205], v[80:81], v[110:111] op_sel_hi:[1,0]
	v_pk_mul_f32 v[202:203], v[78:79], v[110:111] op_sel_hi:[1,0]
	v_pk_mul_f32 v[208:209], v[30:31], v[48:49] op_sel_hi:[1,0]
	v_pk_mul_f32 v[206:207], v[28:29], v[48:49] op_sel_hi:[1,0]
	v_pk_mul_f32 v[112:113], v[84:85], v[110:111] op_sel_hi:[1,0]
	v_pk_mul_f32 v[110:111], v[82:83], v[110:111] op_sel_hi:[1,0]
	s_waitcnt lgkmcnt(0)
	v_mfma_f32_16x16x32_bf16 v[44:47], v[40:43], v[60:63], v[54:57]
	ds_read_b64_tr_b16 v[134:135], v58 offset:27776
	ds_read_b64_tr_b16 v[136:137], v58 offset:32384
	ds_read_b64_tr_b16 v[222:223], v58 offset:18592
	ds_read_b64_tr_b16 v[56:57], v58 offset:23168
	ds_read_b64_tr_b16 v[54:55], v58 offset:18560
	ds_read_b64_tr_b16 v[224:225], v58 offset:23200
	ds_read_b64_tr_b16 v[226:227], v58 offset:27808
	ds_read_b64_tr_b16 v[228:229], v58 offset:32416
	v_mfma_f32_16x16x32_bf16 v[122:125], v[40:43], v[106:109], v[122:125]
	v_mfma_f32_16x16x32_bf16 v[40:43], v[210:213], v[98:101], v[44:47]
	v_mfma_f32_16x16x32_bf16 v[44:47], v[214:217], v[60:63], v[126:129]
	v_mfma_f32_16x16x32_bf16 v[126:129], v[214:217], v[106:109], v[130:133]
	v_mfma_f32_16x16x32_bf16 v[122:125], v[210:213], v[102:105], v[122:125]
	v_mfma_f32_16x16x32_bf16 v[44:47], v[218:221], v[98:101], v[44:47]
	v_mfma_f32_16x16x32_bf16 v[126:129], v[218:221], v[102:105], v[126:129]
	s_waitcnt lgkmcnt(3)
	v_mfma_f32_16x16x32_bf16 v[48:51], v[54:57], v[60:63], v[50:53]
	ds_read_b64_tr_b16 v[212:213], v58 offset:23232
	ds_read_b64_tr_b16 v[214:215], v58 offset:27840
	ds_read_b64_tr_b16 v[216:217], v58 offset:32448
	ds_read_b64_tr_b16 v[210:211], v58 offset:18624
	ds_read_b64_tr_b16 v[218:219], v58 offset:18656
	ds_read_b64_tr_b16 v[220:221], v58 offset:23264
	ds_read_b64_tr_b16 v[230:231], v58 offset:27872
	ds_read_b64_tr_b16 v[232:233], v58 offset:32480
	v_mfma_f32_16x16x32_bf16 v[52:55], v[54:57], v[106:109], v[138:141]
	v_mfma_f32_16x16x32_bf16 v[130:133], v[134:137], v[102:105], v[52:55]
	s_waitcnt lgkmcnt(10)
	v_mfma_f32_16x16x32_bf16 v[52:55], v[222:225], v[60:63], v[142:145]
	v_mfma_f32_16x16x32_bf16 v[56:59], v[222:225], v[106:109], v[158:161]
	v_mfma_f32_16x16x32_bf16 v[48:51], v[134:137], v[98:101], v[48:51]
	s_waitcnt lgkmcnt(8)
	v_mfma_f32_16x16x32_bf16 v[52:55], v[226:229], v[98:101], v[52:55]
	v_mfma_f32_16x16x32_bf16 v[134:137], v[226:229], v[102:105], v[56:59]
	s_waitcnt lgkmcnt(4)
	v_mfma_f32_16x16x32_bf16 v[56:59], v[210:213], v[60:63], v[198:201]
	v_mfma_f32_16x16x32_bf16 v[138:141], v[210:213], v[106:109], v[202:205]
	s_waitcnt lgkmcnt(2)
	v_mfma_f32_16x16x32_bf16 v[60:63], v[218:221], v[60:63], v[206:209]
	v_mfma_f32_16x16x32_bf16 v[106:109], v[218:221], v[106:109], v[110:113]
	v_mfma_f32_16x16x32_bf16 v[56:59], v[214:217], v[98:101], v[56:59]
	v_mfma_f32_16x16x32_bf16 v[138:141], v[214:217], v[102:105], v[138:141]
	s_waitcnt lgkmcnt(0)
	v_mfma_f32_16x16x32_bf16 v[60:63], v[230:233], v[98:101], v[60:63]
	v_mfma_f32_16x16x32_bf16 v[142:145], v[230:233], v[102:105], v[106:109]

.LBB0_1428:
	s_lshl_b32 s40, s74, 9
	s_add_u32 s1, s18, s24
	s_addc_u32 s25, s19, s25
	s_lshl_b32 s41, s74, 8
	s_lshl_b32 s84, s74, 9
	s_add_u32 s24, s1, s84
	s_mov_b32 s1, 0x3fff80
	s_addc_u32 s25, s25, 0
	s_bfe_i32 s26, s0, 0x190000
	v_lshrrev_b32_e32 v248, 1, v166
	v_and_b32_e32 v248, 0x80, v248
	v_and_b32_e32 v249, 15, v166
	v_or_b32_e32 v248, v248, v249
	v_and_b32_e32 v249, 16, v166
	v_lshrrev_b32_e32 v250, 2, v166
	v_and_b32_e32 v250, 8, v250
	v_or_b32_e32 v249, v249, v250
	v_and_b32_e32 v250, 0xc0, v166
	v_or_b32_e32 v249, v249, v250
	v_lshl_or_b32 v248, v248, 10, v249
	v_mov_b32_e32 v249, 0
	v_lshl_add_u64 v[246:247], v[248:249], 1, s[24:25]
	v_mov_b32_e32 v130, 0x3a800000
	s_waitcnt vmcnt(7)
	v_add_f32_e32 v132, v210, v211
	v_add_f32_e32 v133, v212, v213
	v_add_f32_e32 v132, v132, v133
	v_mov_b32_e32 v133, v132
	v_mov_b32_e32 v134, v132
	s_nop 1
	v_permlane32_swap_b32_e32 v133, v134
	v_add_f32_e32 v132, v133, v134
	v_mov_b32_e32 v133, v132
	v_mov_b32_e32 v134, v132
	s_nop 1
	v_permlane16_swap_b32_e32 v133, v134
	v_add_f32_e32 v132, v133, v134
	v_fmaak_f32 v133, v132, v130, 0x3727c5ac
	v_rsq_f32_e32 v134, v133
	v_mul_f32_e32 v133, 0.5, v133
	s_nop 0
	v_mul_f32_e32 v132, v133, v134
	v_fma_f32 v132, -v132, v134, 0.5
	v_fma_f32 v136, v134, v132, v134
	v_mul_f32_e32 v136, 0x3db8aa3b, v136
	v_mov_b32_e32 v137, v136
	v_pk_mul_f32 v[126:127], v[126:127], v[136:137]
	v_pk_mul_f32 v[128:129], v[128:129], v[136:137]
	v_pk_mul_f32 v[122:123], v[122:123], v[136:137]
	v_pk_mul_f32 v[124:125], v[124:125], v[136:137]
	v_pk_mul_f32 v[118:119], v[118:119], v[136:137]
	v_pk_mul_f32 v[120:121], v[120:121], v[136:137]
	v_pk_mul_f32 v[114:115], v[114:115], v[136:137]
	v_pk_mul_f32 v[116:117], v[116:117], v[136:137]
	v_cvt_pk_bf16_f32 v126, v126, v127
	v_cvt_pk_bf16_f32 v127, v128, v129
	v_cvt_pk_bf16_f32 v128, v122, v123
	v_cvt_pk_bf16_f32 v129, v124, v125
	v_cvt_pk_bf16_f32 v118, v118, v119
	v_cvt_pk_bf16_f32 v119, v120, v121
	v_cvt_pk_bf16_f32 v120, v114, v115
	v_cvt_pk_bf16_f32 v121, v116, v117
	s_nop 1
	v_permlane16_swap_b32_e32 v126, v128
	v_permlane16_swap_b32_e32 v127, v129
	v_permlane16_swap_b32_e32 v118, v120
	v_permlane16_swap_b32_e32 v119, v121
	global_store_dwordx4 v[246:247], v[126:129], off
	global_store_dwordx4 v[246:247], v[118:121], off offset:64
	v_add_co_u32_e32 v246, vcc, 0x8000, v246
	s_nop 1
	v_addc_co_u32_e32 v247, vcc, 0, v247, vcc
	s_waitcnt vmcnt(8)
	v_add_f32_e32 v132, v214, v215
	v_add_f32_e32 v133, v216, v217
	v_add_f32_e32 v132, v132, v133
	v_mov_b32_e32 v133, v132
	v_mov_b32_e32 v134, v132
	s_nop 1
	v_permlane32_swap_b32_e32 v133, v134
	v_add_f32_e32 v132, v133, v134
	v_mov_b32_e32 v133, v132
	v_mov_b32_e32 v134, v132
	s_nop 1
	v_permlane16_swap_b32_e32 v133, v134
	v_add_f32_e32 v132, v133, v134
	v_fmaak_f32 v133, v132, v130, 0x3727c5ac
	v_rsq_f32_e32 v134, v133
	v_mul_f32_e32 v133, 0.5, v133
	s_nop 0
	v_mul_f32_e32 v132, v133, v134
	v_fma_f32 v132, -v132, v134, 0.5
	v_fma_f32 v136, v134, v132, v134
	v_mul_f32_e32 v136, 0x3db8aa3b, v136
	v_mov_b32_e32 v137, v136
	v_pk_mul_f32 v[110:111], v[110:111], v[136:137]
	v_pk_mul_f32 v[112:113], v[112:113], v[136:137]
	v_pk_mul_f32 v[106:107], v[106:107], v[136:137]
	v_pk_mul_f32 v[108:109], v[108:109], v[136:137]
	v_pk_mul_f32 v[102:103], v[102:103], v[136:137]
	v_pk_mul_f32 v[104:105], v[104:105], v[136:137]
	v_pk_mul_f32 v[98:99], v[98:99], v[136:137]
	v_pk_mul_f32 v[100:101], v[100:101], v[136:137]
	v_cvt_pk_bf16_f32 v110, v110, v111
	v_cvt_pk_bf16_f32 v111, v112, v113
	v_cvt_pk_bf16_f32 v112, v106, v107
	v_cvt_pk_bf16_f32 v113, v108, v109
	v_cvt_pk_bf16_f32 v102, v102, v103
	v_cvt_pk_bf16_f32 v103, v104, v105
	v_cvt_pk_bf16_f32 v104, v98, v99
	v_cvt_pk_bf16_f32 v105, v100, v101
	s_nop 1
	v_permlane16_swap_b32_e32 v110, v112
	v_permlane16_swap_b32_e32 v111, v113
	v_permlane16_swap_b32_e32 v102, v104
	v_permlane16_swap_b32_e32 v103, v105
	global_store_dwordx4 v[246:247], v[110:113], off
	global_store_dwordx4 v[246:247], v[102:105], off offset:64
	v_add_co_u32_e32 v246, vcc, 0x8000, v246
	s_nop 1
	v_addc_co_u32_e32 v247, vcc, 0, v247, vcc
	s_waitcnt vmcnt(9)
	v_add_f32_e32 v132, v218, v219
	v_add_f32_e32 v133, v220, v221
	v_add_f32_e32 v132, v132, v133
	v_mov_b32_e32 v133, v132
	v_mov_b32_e32 v134, v132
	s_nop 1
	v_permlane32_swap_b32_e32 v133, v134
	v_add_f32_e32 v132, v133, v134
	v_mov_b32_e32 v133, v132
	v_mov_b32_e32 v134, v132
	s_nop 1
	v_permlane16_swap_b32_e32 v133, v134
	v_add_f32_e32 v132, v133, v134
	v_fmaak_f32 v133, v132, v130, 0x3727c5ac
	v_rsq_f32_e32 v134, v133
	v_mul_f32_e32 v133, 0.5, v133
	s_nop 0
	v_mul_f32_e32 v132, v133, v134
	v_fma_f32 v132, -v132, v134, 0.5
	v_fma_f32 v136, v134, v132, v134
	v_mul_f32_e32 v136, 0x3db8aa3b, v136
	v_mov_b32_e32 v137, v136
	v_pk_mul_f32 v[94:95], v[94:95], v[136:137]
	v_pk_mul_f32 v[96:97], v[96:97], v[136:137]
	v_pk_mul_f32 v[90:91], v[90:91], v[136:137]
	v_pk_mul_f32 v[92:93], v[92:93], v[136:137]
	v_pk_mul_f32 v[86:87], v[86:87], v[136:137]
	v_pk_mul_f32 v[88:89], v[88:89], v[136:137]
	v_pk_mul_f32 v[82:83], v[82:83], v[136:137]
	v_pk_mul_f32 v[84:85], v[84:85], v[136:137]
	v_cvt_pk_bf16_f32 v94, v94, v95
	v_cvt_pk_bf16_f32 v95, v96, v97
	v_cvt_pk_bf16_f32 v96, v90, v91
	v_cvt_pk_bf16_f32 v97, v92, v93
	v_cvt_pk_bf16_f32 v86, v86, v87
	v_cvt_pk_bf16_f32 v87, v88, v89
	v_cvt_pk_bf16_f32 v88, v82, v83
	v_cvt_pk_bf16_f32 v89, v84, v85
	s_nop 1
	v_permlane16_swap_b32_e32 v94, v96
	v_permlane16_swap_b32_e32 v95, v97
	v_permlane16_swap_b32_e32 v86, v88
	v_permlane16_swap_b32_e32 v87, v89
	global_store_dwordx4 v[246:247], v[94:97], off
	global_store_dwordx4 v[246:247], v[86:89], off offset:64
	v_add_co_u32_e32 v246, vcc, 0x8000, v246
	s_nop 1
	v_addc_co_u32_e32 v247, vcc, 0, v247, vcc
	s_waitcnt vmcnt(10)
	v_add_f32_e32 v132, v222, v223
	v_add_f32_e32 v133, v224, v225
	v_add_f32_e32 v132, v132, v133
	v_mov_b32_e32 v133, v132
	v_mov_b32_e32 v134, v132
	s_nop 1
	v_permlane32_swap_b32_e32 v133, v134
	v_add_f32_e32 v132, v133, v134
	v_mov_b32_e32 v133, v132
	v_mov_b32_e32 v134, v132
	s_nop 1
	v_permlane16_swap_b32_e32 v133, v134
	v_add_f32_e32 v132, v133, v134
	v_fmaak_f32 v133, v132, v130, 0x3727c5ac
	v_rsq_f32_e32 v134, v133
	v_mul_f32_e32 v133, 0.5, v133
	s_nop 0
	v_mul_f32_e32 v132, v133, v134
	v_fma_f32 v132, -v132, v134, 0.5
	v_fma_f32 v136, v134, v132, v134
	v_mul_f32_e32 v136, 0x3db8aa3b, v136
	v_mov_b32_e32 v137, v136
	v_pk_mul_f32 v[78:79], v[78:79], v[136:137]
	v_pk_mul_f32 v[80:81], v[80:81], v[136:137]
	v_pk_mul_f32 v[74:75], v[74:75], v[136:137]
	v_pk_mul_f32 v[76:77], v[76:77], v[136:137]
	v_pk_mul_f32 v[70:71], v[70:71], v[136:137]
	v_pk_mul_f32 v[72:73], v[72:73], v[136:137]
	v_pk_mul_f32 v[66:67], v[66:67], v[136:137]
	v_pk_mul_f32 v[68:69], v[68:69], v[136:137]
	v_cvt_pk_bf16_f32 v78, v78, v79
	v_cvt_pk_bf16_f32 v79, v80, v81
	v_cvt_pk_bf16_f32 v80, v74, v75
	v_cvt_pk_bf16_f32 v81, v76, v77
	v_cvt_pk_bf16_f32 v70, v70, v71
	v_cvt_pk_bf16_f32 v71, v72, v73
	v_cvt_pk_bf16_f32 v72, v66, v67
	v_cvt_pk_bf16_f32 v73, v68, v69
	s_nop 1
	v_permlane16_swap_b32_e32 v78, v80
	v_permlane16_swap_b32_e32 v79, v81
	v_permlane16_swap_b32_e32 v70, v72
	v_permlane16_swap_b32_e32 v71, v73
	global_store_dwordx4 v[246:247], v[78:81], off
	global_store_dwordx4 v[246:247], v[70:73], off offset:64
	v_add_co_u32_e32 v246, vcc, 0x8000, v246
	s_nop 1
	v_addc_co_u32_e32 v247, vcc, 0, v247, vcc
	s_waitcnt vmcnt(11)
	v_add_f32_e32 v132, v226, v227
	v_add_f32_e32 v133, v228, v229
	v_add_f32_e32 v132, v132, v133
	v_mov_b32_e32 v133, v132
	v_mov_b32_e32 v134, v132
	s_nop 1
	v_permlane32_swap_b32_e32 v133, v134
	v_add_f32_e32 v132, v133, v134
	v_mov_b32_e32 v133, v132
	v_mov_b32_e32 v134, v132
	s_nop 1
	v_permlane16_swap_b32_e32 v133, v134
	v_add_f32_e32 v132, v133, v134
	v_fmaak_f32 v133, v132, v130, 0x3727c5ac
	v_rsq_f32_e32 v134, v133
	v_mul_f32_e32 v133, 0.5, v133
	s_nop 0
	v_mul_f32_e32 v132, v133, v134
	v_fma_f32 v132, -v132, v134, 0.5
	v_fma_f32 v136, v134, v132, v134
	v_mul_f32_e32 v136, 0x3db8aa3b, v136
	v_mov_b32_e32 v137, v136
	v_pk_mul_f32 v[60:61], v[60:61], v[136:137]
	v_pk_mul_f32 v[62:63], v[62:63], v[136:137]
	v_pk_mul_f32 v[56:57], v[56:57], v[136:137]
	v_pk_mul_f32 v[58:59], v[58:59], v[136:137]
	v_pk_mul_f32 v[52:53], v[52:53], v[136:137]
	v_pk_mul_f32 v[54:55], v[54:55], v[136:137]
	v_pk_mul_f32 v[48:49], v[48:49], v[136:137]
	v_pk_mul_f32 v[50:51], v[50:51], v[136:137]
	v_cvt_pk_bf16_f32 v60, v60, v61
	v_cvt_pk_bf16_f32 v61, v62, v63
	v_cvt_pk_bf16_f32 v62, v56, v57
	v_cvt_pk_bf16_f32 v63, v58, v59
	v_cvt_pk_bf16_f32 v52, v52, v53
	v_cvt_pk_bf16_f32 v53, v54, v55
	v_cvt_pk_bf16_f32 v54, v48, v49
	v_cvt_pk_bf16_f32 v55, v50, v51
	s_nop 1
	v_permlane16_swap_b32_e32 v60, v62
	v_permlane16_swap_b32_e32 v61, v63
	v_permlane16_swap_b32_e32 v52, v54
	v_permlane16_swap_b32_e32 v53, v55
	global_store_dwordx4 v[246:247], v[60:63], off
	global_store_dwordx4 v[246:247], v[52:55], off offset:64
	v_add_co_u32_e32 v246, vcc, 0x8000, v246
	s_nop 1
	v_addc_co_u32_e32 v247, vcc, 0, v247, vcc
	s_waitcnt vmcnt(12)
	v_add_f32_e32 v132, v230, v231
	v_add_f32_e32 v133, v232, v233
	v_add_f32_e32 v132, v132, v133
	v_mov_b32_e32 v133, v132
	v_mov_b32_e32 v134, v132
	s_nop 1
	v_permlane32_swap_b32_e32 v133, v134
	v_add_f32_e32 v132, v133, v134
	v_mov_b32_e32 v133, v132
	v_mov_b32_e32 v134, v132
	s_nop 1
	v_permlane16_swap_b32_e32 v133, v134
	v_add_f32_e32 v132, v133, v134
	v_fmaak_f32 v133, v132, v130, 0x3727c5ac
	v_rsq_f32_e32 v134, v133
	v_mul_f32_e32 v133, 0.5, v133
	s_nop 0
	v_mul_f32_e32 v132, v133, v134
	v_fma_f32 v132, -v132, v134, 0.5
	v_fma_f32 v136, v134, v132, v134
	v_mul_f32_e32 v136, 0x3db8aa3b, v136
	v_mov_b32_e32 v137, v136
	v_pk_mul_f32 v[44:45], v[44:45], v[136:137]
	v_pk_mul_f32 v[46:47], v[46:47], v[136:137]
	v_pk_mul_f32 v[40:41], v[40:41], v[136:137]
	v_pk_mul_f32 v[42:43], v[42:43], v[136:137]
	v_pk_mul_f32 v[36:37], v[36:37], v[136:137]
	v_pk_mul_f32 v[38:39], v[38:39], v[136:137]
	v_pk_mul_f32 v[32:33], v[32:33], v[136:137]
	v_pk_mul_f32 v[34:35], v[34:35], v[136:137]
	v_cvt_pk_bf16_f32 v44, v44, v45
	v_cvt_pk_bf16_f32 v45, v46, v47
	v_cvt_pk_bf16_f32 v46, v40, v41
	v_cvt_pk_bf16_f32 v47, v42, v43
	v_cvt_pk_bf16_f32 v36, v36, v37
	v_cvt_pk_bf16_f32 v37, v38, v39
	v_cvt_pk_bf16_f32 v38, v32, v33
	v_cvt_pk_bf16_f32 v39, v34, v35
	s_nop 1
	v_permlane16_swap_b32_e32 v44, v46
	v_permlane16_swap_b32_e32 v45, v47
	v_permlane16_swap_b32_e32 v36, v38
	v_permlane16_swap_b32_e32 v37, v39
	global_store_dwordx4 v[246:247], v[44:47], off
	global_store_dwordx4 v[246:247], v[36:39], off offset:64
	v_add_co_u32_e32 v246, vcc, 0x8000, v246
	s_nop 1
	v_addc_co_u32_e32 v247, vcc, 0, v247, vcc
	s_waitcnt vmcnt(13)
	v_add_f32_e32 v132, v234, v235
	v_add_f32_e32 v133, v236, v237
	v_add_f32_e32 v132, v132, v133
	v_mov_b32_e32 v133, v132
	v_mov_b32_e32 v134, v132
	s_nop 1
	v_permlane32_swap_b32_e32 v133, v134
	v_add_f32_e32 v132, v133, v134
	v_mov_b32_e32 v133, v132
	v_mov_b32_e32 v134, v132
	s_nop 1
	v_permlane16_swap_b32_e32 v133, v134
	v_add_f32_e32 v132, v133, v134
	v_fmaak_f32 v133, v132, v130, 0x3727c5ac
	v_rsq_f32_e32 v134, v133
	v_mul_f32_e32 v133, 0.5, v133
	s_nop 0
	v_mul_f32_e32 v132, v133, v134
	v_fma_f32 v132, -v132, v134, 0.5
	v_fma_f32 v136, v134, v132, v134
	v_mul_f32_e32 v136, 0x3db8aa3b, v136
	v_mov_b32_e32 v137, v136
	v_pk_mul_f32 v[24:25], v[24:25], v[136:137]
	v_pk_mul_f32 v[26:27], v[26:27], v[136:137]
	v_pk_mul_f32 v[20:21], v[20:21], v[136:137]
	v_pk_mul_f32 v[22:23], v[22:23], v[136:137]
	v_pk_mul_f32 v[16:17], v[16:17], v[136:137]
	v_pk_mul_f32 v[18:19], v[18:19], v[136:137]
	v_pk_mul_f32 v[12:13], v[12:13], v[136:137]
	v_pk_mul_f32 v[14:15], v[14:15], v[136:137]
	v_cvt_pk_bf16_f32 v24, v24, v25
	v_cvt_pk_bf16_f32 v25, v26, v27
	v_cvt_pk_bf16_f32 v26, v20, v21
	v_cvt_pk_bf16_f32 v27, v22, v23
	v_cvt_pk_bf16_f32 v16, v16, v17
	v_cvt_pk_bf16_f32 v17, v18, v19
	v_cvt_pk_bf16_f32 v18, v12, v13
	v_cvt_pk_bf16_f32 v19, v14, v15
	s_nop 1
	v_permlane16_swap_b32_e32 v24, v26
	v_permlane16_swap_b32_e32 v25, v27
	v_permlane16_swap_b32_e32 v16, v18
	v_permlane16_swap_b32_e32 v17, v19
	global_store_dwordx4 v[246:247], v[24:27], off
	global_store_dwordx4 v[246:247], v[16:19], off offset:64
	v_add_co_u32_e32 v246, vcc, 0x8000, v246
	s_nop 1
	v_addc_co_u32_e32 v247, vcc, 0, v247, vcc
	s_waitcnt vmcnt(14)
	v_add_f32_e32 v132, v252, v253
	v_add_f32_e32 v133, v254, v255
	v_add_f32_e32 v132, v132, v133
	v_mov_b32_e32 v133, v132
	v_mov_b32_e32 v134, v132
	s_nop 1
	v_permlane32_swap_b32_e32 v133, v134
	v_add_f32_e32 v132, v133, v134
	v_mov_b32_e32 v133, v132
	v_mov_b32_e32 v134, v132
	s_nop 1
	v_permlane16_swap_b32_e32 v133, v134
	v_add_f32_e32 v132, v133, v134
	v_fmaak_f32 v133, v132, v130, 0x3727c5ac
	v_rsq_f32_e32 v134, v133
	v_mul_f32_e32 v133, 0.5, v133
	s_nop 0
	v_mul_f32_e32 v132, v133, v134
	v_fma_f32 v132, -v132, v134, 0.5
	v_fma_f32 v136, v134, v132, v134
	v_mul_f32_e32 v136, 0x3db8aa3b, v136
	v_mov_b32_e32 v137, v136
	v_pk_mul_f32 v[8:9], v[8:9], v[136:137]
	v_pk_mul_f32 v[10:11], v[10:11], v[136:137]
	v_pk_mul_f32 v[4:5], v[4:5], v[136:137]
	v_pk_mul_f32 v[6:7], v[6:7], v[136:137]
	v_pk_mul_f32 v[0:1], v[0:1], v[136:137]
	v_pk_mul_f32 v[2:3], v[2:3], v[136:137]
	v_pk_mul_f32 v[28:29], v[28:29], v[136:137]
	v_pk_mul_f32 v[30:31], v[30:31], v[136:137]
	v_cvt_pk_bf16_f32 v8, v8, v9
	v_cvt_pk_bf16_f32 v9, v10, v11
	v_cvt_pk_bf16_f32 v10, v4, v5
	v_cvt_pk_bf16_f32 v11, v6, v7
	v_cvt_pk_bf16_f32 v0, v0, v1
	v_cvt_pk_bf16_f32 v1, v2, v3
	v_cvt_pk_bf16_f32 v2, v28, v29
	v_cvt_pk_bf16_f32 v3, v30, v31
	s_nop 1
	v_permlane16_swap_b32_e32 v8, v10
	v_permlane16_swap_b32_e32 v9, v11
	v_permlane16_swap_b32_e32 v0, v2
	v_permlane16_swap_b32_e32 v1, v3
	global_store_dwordx4 v[246:247], v[8:11], off
	global_store_dwordx4 v[246:247], v[0:3], off offset:64
	v_mov_b32_e32 v90, v166
	s_waitcnt vmcnt(0)
	s_barrier
	s_add_i32 s0, s26, s44
	v_ashrrev_i32_e32 v32, 31, v90
	s_ashr_i32 s1, s0, 31
	s_ashr_i32 s27, s26, 31
	v_lshrrev_b32_e32 v32, 27, v32
	s_lshl_b64 s[0:1], s[0:1], 20
	s_lshl_b64 s[24:25], s[26:27], 12
	s_lshl_b32 s27, s65, 8
	v_readlane_b32 s2, v241, 44
	v_add_u32_e32 v32, v90, v32
	s_add_u32 s0, s2, s0
	v_readlane_b32 s2, v241, 45
	v_ashrrev_i32_e32 v66, 5, v32
	v_and_b32_e32 v32, 0xffffffe0, v32
	s_addc_u32 s1, s2, s1
	v_sub_u32_e32 v93, v90, v32
	s_add_u32 s0, s0, s84
	v_ashrrev_i32_e32 v67, 31, v66
	v_lshlrev_b32_e32 v34, 3, v93
	s_addc_u32 s1, s1, 0
	v_lshlrev_b64 v[68:69], 12, v[66:67]
	v_ashrrev_i32_e32 v35, 31, v34
	v_lshl_add_u64 v[32:33], s[0:1], 0, v[68:69]
	v_lshlrev_b64 v[70:71], 1, v[34:35]
	v_lshl_add_u64 v[36:37], v[32:33], 0, v[70:71]
	v_add_u32_e32 v32, 0x200, v90
	v_ashrrev_i32_e32 v33, 31, v32
	v_lshrrev_b32_e32 v33, 27, v33
	v_add_u32_e32 v33, v32, v33
	v_ashrrev_i32_e32 v72, 5, v33
	v_and_b32_e32 v33, 0xffffffe0, v33
	v_sub_u32_e32 v67, v32, v33
	v_ashrrev_i32_e32 v73, 31, v72
	v_lshlrev_b32_e32 v34, 3, v67
	v_lshlrev_b64 v[74:75], 12, v[72:73]
	v_ashrrev_i32_e32 v35, 31, v34
	v_lshl_add_u64 v[32:33], s[0:1], 0, v[74:75]
	v_lshlrev_b64 v[76:77], 1, v[34:35]
	v_lshl_add_u64 v[44:45], v[32:33], 0, v[76:77]
	v_add_u32_e32 v32, 0x400, v90
	v_ashrrev_i32_e32 v33, 31, v32
	v_lshrrev_b32_e32 v33, 27, v33
	v_add_u32_e32 v33, v32, v33
	v_ashrrev_i32_e32 v78, 5, v33
	v_and_b32_e32 v33, 0xffffffe0, v33
	v_sub_u32_e32 v73, v32, v33
	v_ashrrev_i32_e32 v79, 31, v78
	v_lshlrev_b32_e32 v34, 3, v73
	v_lshlrev_b64 v[80:81], 12, v[78:79]
	v_ashrrev_i32_e32 v35, 31, v34
	v_lshl_add_u64 v[32:33], s[0:1], 0, v[80:81]
	v_lshlrev_b64 v[82:83], 1, v[34:35]
	v_lshl_add_u64 v[52:53], v[32:33], 0, v[82:83]
	v_add_u32_e32 v32, 0x600, v90
	v_ashrrev_i32_e32 v33, 31, v32
	v_and_b32_e32 v91, 15, v90
	v_ashrrev_i32_e32 v0, 2, v90
	v_lshrrev_b32_e32 v33, 27, v33
	v_and_b32_e32 v0, -16, v0
	v_or_b32_e32 v2, s27, v91
	v_add_u32_e32 v33, v32, v33
	v_ashrrev_i32_e32 v1, 31, v0
	v_or_b32_e32 v2, s24, v2
	v_mov_b32_e32 v3, s25
	v_ashrrev_i32_e32 v84, 5, v33
	v_and_b32_e32 v33, 0xffffffe0, v33
	v_lshl_add_u64 v[0:1], v[2:3], 0, v[0:1]
	v_sub_u32_e32 v79, v32, v33
	v_lshlrev_b64 v[138:139], 11, v[0:1]
	v_ashrrev_i32_e32 v85, 31, v84
	v_lshlrev_b32_e32 v34, 3, v79
	v_bfe_u32 v92, v90, 4, 2
	v_lshl_add_u64 v[0:1], s[18:19], 0, v[138:139]
	v_lshlrev_b64 v[86:87], 12, v[84:85]
	v_ashrrev_i32_e32 v35, 31, v34
	v_lshl_add_u64 v[0:1], v[0:1], 0, s[84:85]
	v_lshlrev_b32_e32 v64, 4, v92
	v_lshl_add_u64 v[32:33], s[0:1], 0, v[86:87]
	v_lshlrev_b64 v[88:89], 1, v[34:35]
	v_lshl_add_u64 v[28:29], v[0:1], 0, v[64:65]
	v_lshl_add_u64 v[60:61], v[32:33], 0, v[88:89]
	global_load_dwordx4 v[0:3], v[28:29], off
	global_load_dwordx4 v[4:7], v[28:29], off offset:64
	global_load_dwordx4 v[8:11], v[28:29], off offset:128
	global_load_dwordx4 v[12:15], v[28:29], off offset:192
	global_load_dwordx4 v[16:19], v[28:29], off offset:256
	global_load_dwordx4 v[20:23], v[28:29], off offset:320
	global_load_dwordx4 v[24:27], v[28:29], off offset:384
	s_nop 0
	global_load_dwordx4 v[28:31], v[28:29], off offset:448
	s_nop 0
	global_load_dwordx4 v[32:35], v[36:37], off
	s_nop 0
	global_load_dwordx4 v[36:39], v[36:37], off offset:2048
	s_nop 0
	global_load_dwordx4 v[40:43], v[44:45], off
	s_nop 0
	global_load_dwordx4 v[44:47], v[44:45], off offset:2048
	s_nop 0
	global_load_dwordx4 v[48:51], v[52:53], off
	s_nop 0
	global_load_dwordx4 v[52:55], v[52:53], off offset:2048
	s_nop 0
	global_load_dwordx4 v[56:59], v[60:61], off
	s_nop 0
	global_load_dwordx4 v[60:63], v[60:61], off offset:2048
	s_movk_i32 s2, 0x210
	v_mul_lo_u32 v151, v66, s2
	v_cmp_lt_i32_e32 vcc, v157, v168
	v_lshlrev_b32_e32 v160, 4, v73
	v_lshl_add_u32 v73, v66, 4, v151
	v_cndmask_b32_e32 v66, v155, v157, vcc
	v_cmp_lt_i32_e32 vcc, v169, v168
	v_lshlrev_b32_e32 v148, 2, v66
	v_lshlrev_b32_e32 v150, 2, v92
	v_cndmask_b32_e32 v66, v155, v169, vcc
	v_lshlrev_b32_e32 v149, 2, v66
	v_bfe_u32 v66, v90, 2, 2
	s_add_i32 s28, s73, s26
	v_or_b32_e32 v66, v150, v66
	s_ashr_i32 s29, s28, 31
	v_lshlrev_b32_e32 v158, 4, v67
	v_mul_u32_u24_e32 v66, 0x220, v66
	v_lshlrev_b32_e32 v67, 3, v90
	s_lshl_b64 s[28:29], s[28:29], 20
	v_and_or_b32 v163, v67, 24, v66
	v_lshl_add_u64 v[66:67], s[28:29], 0, v[86:87]
	v_or_b32_e32 v66, s40, v66
	v_lshl_add_u64 v[66:67], v[66:67], 0, v[88:89]
	v_lshl_add_u64 v[140:141], s[68:69], 0, v[66:67]
	v_lshl_add_u64 v[66:67], s[28:29], 0, v[80:81]
	v_or_b32_e32 v66, s40, v66
	v_lshl_add_u64 v[66:67], v[66:67], 0, v[82:83]
	v_lshl_add_u64 v[142:143], s[68:69], 0, v[66:67]
	v_lshl_add_u64 v[66:67], s[28:29], 0, v[74:75]
	v_or_b32_e32 v66, s40, v66
	v_lshl_add_u64 v[66:67], v[66:67], 0, v[76:77]
	v_lshl_add_u64 v[144:145], s[68:69], 0, v[66:67]
	v_lshl_add_u64 v[66:67], s[28:29], 0, v[68:69]
	v_mul_lo_u32 v153, v72, s2
	v_mul_lo_u32 v159, v78, s2
	v_mul_lo_u32 v161, v84, s2
	v_or_b32_e32 v66, s40, v66
	v_lshlrev_b32_e32 v152, 4, v93
	v_lshlrev_b32_e32 v162, 4, v79
	v_lshl_add_u32 v72, v72, 4, v153
	v_lshl_add_u32 v78, v78, 4, v159
	v_lshl_add_u32 v79, v84, 4, v161
	v_mul_u32_u24_e32 v84, 0x210, v91
	v_lshl_add_u64 v[66:67], v[66:67], 0, v[70:71]
	v_mov_b32_e32 v130, 0
	v_lshl_add_u64 v[146:147], s[68:69], 0, v[66:67]
	v_mov_b32_e32 v131, 0xff800000
	s_mov_b64 s[30:31], 0
	v_add_u32_e32 v164, v73, v152
	v_add_u32_e32 v165, v72, v158
	v_add_u32_e32 v197, v78, v160
	v_add_u32_e32 v198, v79, v162
	v_add_u32_e32 v199, v84, v64
	v_mov_b32_e32 v98, 0
	v_mov_b32_e32 v99, v130
	v_mov_b32_e32 v100, v130
	v_mov_b32_e32 v101, v130
	v_mov_b32_e32 v102, 0
	v_mov_b32_e32 v103, v130
	v_mov_b32_e32 v104, v130
	v_mov_b32_e32 v105, v130
	v_mov_b32_e32 v90, 0
	v_mov_b32_e32 v91, v130
	v_mov_b32_e32 v92, v130
	v_mov_b32_e32 v93, v130
	v_mov_b32_e32 v94, 0
	v_mov_b32_e32 v95, v130
	v_mov_b32_e32 v96, v130
	v_mov_b32_e32 v97, v130
	v_mov_b32_e32 v78, 0
	v_mov_b32_e32 v79, v130
	v_mov_b32_e32 v80, v130
	v_mov_b32_e32 v81, v130
	v_mov_b32_e32 v86, 0
	v_mov_b32_e32 v87, v130
	v_mov_b32_e32 v88, v130
	v_mov_b32_e32 v89, v130
	v_mov_b32_e32 v82, 0
	v_mov_b32_e32 v83, v130
	v_mov_b32_e32 v84, v130
	v_mov_b32_e32 v85, v130
	v_mov_b32_e32 v106, 0
	v_mov_b32_e32 v107, v130
	v_mov_b32_e32 v108, v130
	v_mov_b32_e32 v109, v130
	v_mov_b32_e32 v110, 0
	v_mov_b32_e32 v111, v130
	v_mov_b32_e32 v112, v130
	v_mov_b32_e32 v113, v130
	v_mov_b32_e32 v114, 0
	v_mov_b32_e32 v115, v130
	v_mov_b32_e32 v116, v130
	v_mov_b32_e32 v117, v130
	v_mov_b32_e32 v66, 0
	v_mov_b32_e32 v67, v130
	v_mov_b32_e32 v68, v130
	v_mov_b32_e32 v69, v130
	v_mov_b32_e32 v74, 0
	v_mov_b32_e32 v75, v130
	v_mov_b32_e32 v76, v130
	v_mov_b32_e32 v77, v130
	v_mov_b32_e32 v118, 0
	v_mov_b32_e32 v119, v130
	v_mov_b32_e32 v120, v130
	v_mov_b32_e32 v121, v130
	v_mov_b32_e32 v122, 0
	v_mov_b32_e32 v123, v130
	v_mov_b32_e32 v124, v130
	v_mov_b32_e32 v125, v130
	v_mov_b32_e32 v126, 0
	v_mov_b32_e32 v127, v130
	v_mov_b32_e32 v128, v130
	v_mov_b32_e32 v129, v130
	v_mov_b32_e32 v70, 0
	v_mov_b32_e32 v71, v130
	v_mov_b32_e32 v72, v130
	v_mov_b32_e32 v73, v130

.LBB0_1431:
	ds_read_b128 v[132:135], v199
	ds_read_b128 v[200:203], v199 offset:64
	ds_read_b128 v[204:207], v199 offset:128
	ds_read_b128 v[208:211], v199 offset:192
	ds_read_b128 v[212:215], v199 offset:384
	ds_read_b128 v[216:219], v199 offset:448
	s_waitcnt lgkmcnt(5)
	v_mfma_f32_16x16x32_bf16 v[132:135], v[132:135], v[0:3], 0
	s_waitcnt lgkmcnt(4)
	v_mfma_f32_16x16x32_bf16 v[132:135], v[200:203], v[4:7], v[132:135]
	ds_read_b128 v[200:203], v199 offset:256
	s_waitcnt lgkmcnt(4)
	v_mfma_f32_16x16x32_bf16 v[132:135], v[204:207], v[8:11], v[132:135]
	ds_read_b128 v[204:207], v199 offset:320
	s_waitcnt lgkmcnt(4)
	v_mfma_f32_16x16x32_bf16 v[132:135], v[208:211], v[12:15], v[132:135]
	s_waitcnt lgkmcnt(1)
	v_mfma_f32_16x16x32_bf16 v[132:135], v[200:203], v[16:19], v[132:135]
	ds_read_b128 v[200:203], v199 offset:8448
	ds_read_b128 v[208:211], v199 offset:8512
	ds_read_b128 v[220:223], v199 offset:8576
	ds_read_b128 v[224:227], v199 offset:8640
	s_waitcnt lgkmcnt(4)
	v_mfma_f32_16x16x32_bf16 v[132:135], v[204:207], v[20:23], v[132:135]
	v_mfma_f32_16x16x32_bf16 v[132:135], v[212:215], v[24:27], v[132:135]
	v_mfma_f32_16x16x32_bf16 v[132:135], v[216:219], v[28:31], v[132:135]
	s_waitcnt lgkmcnt(3)
	v_mfma_f32_16x16x32_bf16 v[200:203], v[200:203], v[0:3], 0
	ds_read_b128 v[204:207], v199 offset:8704
	ds_read_b128 v[212:215], v199 offset:8768
	ds_read_b128 v[216:219], v199 offset:8832
	ds_read_b128 v[228:231], v199 offset:8896
	s_waitcnt lgkmcnt(6)
	v_mfma_f32_16x16x32_bf16 v[200:203], v[208:211], v[4:7], v[200:203]
	s_waitcnt lgkmcnt(5)
	v_mfma_f32_16x16x32_bf16 v[200:203], v[220:223], v[8:11], v[200:203]
	s_waitcnt lgkmcnt(4)
	v_mfma_f32_16x16x32_bf16 v[200:203], v[224:227], v[12:15], v[200:203]
	s_waitcnt lgkmcnt(3)
	v_mfma_f32_16x16x32_bf16 v[200:203], v[204:207], v[16:19], v[200:203]
	ds_read_b128 v[204:207], v199 offset:16896
	ds_read_b128 v[208:211], v199 offset:16960
	ds_read_b128 v[220:223], v199 offset:17024
	ds_read_b128 v[224:227], v199 offset:17088
	s_waitcnt lgkmcnt(6)
	v_mfma_f32_16x16x32_bf16 v[200:203], v[212:215], v[20:23], v[200:203]
	s_waitcnt lgkmcnt(5)
	v_mfma_f32_16x16x32_bf16 v[200:203], v[216:219], v[24:27], v[200:203]
	s_waitcnt lgkmcnt(4)
	v_mfma_f32_16x16x32_bf16 v[212:215], v[228:231], v[28:31], v[200:203]
	s_waitcnt lgkmcnt(3)
	v_mfma_f32_16x16x32_bf16 v[200:203], v[204:207], v[0:3], 0
	ds_read_b128 v[204:207], v199 offset:17152
	ds_read_b128 v[216:219], v199 offset:17216
	ds_read_b128 v[228:231], v199 offset:17280
	ds_read_b128 v[232:235], v199 offset:17344
	s_waitcnt lgkmcnt(6)
	v_mfma_f32_16x16x32_bf16 v[200:203], v[208:211], v[4:7], v[200:203]
	s_waitcnt lgkmcnt(5)
	v_mfma_f32_16x16x32_bf16 v[200:203], v[220:223], v[8:11], v[200:203]
	s_waitcnt lgkmcnt(4)
	v_mfma_f32_16x16x32_bf16 v[200:203], v[224:227], v[12:15], v[200:203]
	s_waitcnt lgkmcnt(3)
	v_mfma_f32_16x16x32_bf16 v[200:203], v[204:207], v[16:19], v[200:203]
	ds_read_b128 v[204:207], v199 offset:25344
	ds_read_b128 v[208:211], v199 offset:25408
	ds_read_b128 v[220:223], v199 offset:25472
	ds_read_b128 v[224:227], v199 offset:25536
	s_waitcnt lgkmcnt(6)
	v_mfma_f32_16x16x32_bf16 v[200:203], v[216:219], v[20:23], v[200:203]
	s_waitcnt lgkmcnt(5)
	v_mfma_f32_16x16x32_bf16 v[200:203], v[228:231], v[24:27], v[200:203]
	s_waitcnt lgkmcnt(4)
	v_mfma_f32_16x16x32_bf16 v[216:219], v[232:235], v[28:31], v[200:203]
	s_waitcnt lgkmcnt(3)
	v_mfma_f32_16x16x32_bf16 v[200:203], v[204:207], v[0:3], 0
	ds_read_b128 v[204:207], v199 offset:25600
	ds_read_b128 v[228:231], v199 offset:25664
	ds_read_b128 v[232:235], v199 offset:25728
	ds_read_b128 v[236:239], v199 offset:25792
	s_waitcnt lgkmcnt(6)
	v_mfma_f32_16x16x32_bf16 v[200:203], v[208:211], v[4:7], v[200:203]
	s_waitcnt lgkmcnt(5)
	v_mfma_f32_16x16x32_bf16 v[200:203], v[220:223], v[8:11], v[200:203]
	s_waitcnt lgkmcnt(4)
	v_mfma_f32_16x16x32_bf16 v[200:203], v[224:227], v[12:15], v[200:203]
	s_waitcnt lgkmcnt(3)
	v_mfma_f32_16x16x32_bf16 v[200:203], v[204:207], v[16:19], v[200:203]
	s_waitcnt lgkmcnt(2)
	v_mfma_f32_16x16x32_bf16 v[200:203], v[228:231], v[20:23], v[200:203]
	s_waitcnt lgkmcnt(1)
	v_mfma_f32_16x16x32_bf16 v[200:203], v[232:235], v[24:27], v[200:203]
	s_waitcnt lgkmcnt(0)
	v_mfma_f32_16x16x32_bf16 v[202:205], v[236:239], v[28:31], v[200:203]
	v_max3_f32 v64, v132, s33, v133
	v_max3_f32 v64, v64, v134, v135
	v_max3_f32 v64, v64, v212, v213
	v_max3_f32 v64, v64, v214, v215
	v_max3_f32 v64, v64, v216, v217
	v_max3_f32 v64, v64, v218, v219
	s_nop 1
	v_max3_f32 v64, v64, v202, v203
	v_max3_f32 v64, v64, v204, v205
	ds_bpermute_b32 v136, v148, v64
	ds_read_b64_tr_b16 v[220:221], v163 offset:42592
	s_waitcnt lgkmcnt(1)
	v_max_f32_e32 v136, v136, v136
	v_max_f32_e32 v64, v64, v136
	ds_bpermute_b32 v136, v149, v64
	s_waitcnt lgkmcnt(0)
	v_max3_f32 v200, v131, v64, v136
	v_cmp_neq_f32_e32 vcc, s33, v200
	s_nop 1
	v_cndmask_b32_e32 v136, 0, v200, vcc
	v_sub_f32_e32 v201, v213, v136
	v_exp_f32_e32 v206, v201
	v_sub_f32_e32 v201, v214, v136
	v_sub_f32_e32 v64, v131, v136
	v_sub_f32_e32 v131, v132, v136
	v_exp_f32_e32 v207, v201
	v_sub_f32_e32 v201, v215, v136
	v_sub_f32_e32 v132, v133, v136
	v_sub_f32_e32 v133, v134, v136
	v_exp_f32_e32 v131, v131
	v_exp_f32_e32 v208, v201
	v_sub_f32_e32 v201, v216, v136
	v_exp_f32_e32 v132, v132
	v_sub_f32_e32 v134, v135, v136
	v_exp_f32_e32 v133, v133
	v_sub_f32_e32 v137, v212, v136
	v_exp_f32_e32 v209, v201
	v_sub_f32_e32 v201, v217, v136
	v_exp_f32_e32 v134, v134
	v_add_f32_e32 v135, 0, v131
	v_exp_f32_e32 v137, v137
	v_exp_f32_e32 v210, v201
	v_sub_f32_e32 v201, v218, v136
	v_add_f32_e32 v135, v132, v135
	v_add_f32_e32 v135, v133, v135
	v_exp_f32_e32 v211, v201
	v_sub_f32_e32 v201, v219, v136
	v_add_f32_e32 v135, v134, v135
	v_add_f32_e32 v135, v137, v135
	v_exp_f32_e32 v212, v201
	v_sub_f32_e32 v201, v202, v136
	v_add_f32_e32 v135, v206, v135
	v_add_f32_e32 v135, v207, v135
	v_exp_f32_e32 v202, v201
	v_sub_f32_e32 v201, v203, v136
	v_add_f32_e32 v135, v208, v135
	v_add_f32_e32 v135, v209, v135
	v_exp_f32_e32 v203, v201
	v_sub_f32_e32 v201, v204, v136
	v_add_f32_e32 v135, v210, v135
	v_sub_f32_e32 v136, v205, v136
	v_add_f32_e32 v135, v211, v135
	v_exp_f32_e32 v204, v201
	v_add_f32_e32 v135, v212, v135
	v_exp_f32_e32 v205, v136
	v_exp_f32_e32 v64, v64
	v_add_f32_e32 v135, v202, v135
	v_add_f32_e32 v135, v203, v135
	v_add_f32_e32 v135, v204, v135
	v_add_f32_e32 v201, v205, v135
	v_fmac_f32_e32 v201, v130, v64
	v_cvt_pk_bf16_f32 v130, v131, v132
	v_cvt_pk_bf16_f32 v132, v137, v206
	v_cvt_pk_bf16_f32 v136, v202, v203
	v_cvt_pk_bf16_f32 v137, v204, v205
	ds_read_b64_tr_b16 v[202:203], v163 offset:33824
	ds_read_b64_tr_b16 v[204:205], v163 offset:42528
	v_cvt_pk_bf16_f32 v131, v133, v134
	v_cvt_pk_bf16_f32 v133, v207, v208
	v_cvt_pk_bf16_f32 v134, v209, v210
	ds_read_b64_tr_b16 v[206:207], v163 offset:51232
	ds_read_b64_tr_b16 v[208:209], v163 offset:59936
	v_pk_mul_f32 v[68:69], v[68:69], v[64:65] op_sel_hi:[1,0]
	v_pk_mul_f32 v[66:67], v[66:67], v[64:65] op_sel_hi:[1,0]
	v_cvt_pk_bf16_f32 v135, v211, v212
	v_pk_mul_f32 v[76:77], v[76:77], v[64:65] op_sel_hi:[1,0]
	s_waitcnt lgkmcnt(2)
	v_mfma_f32_16x16x32_bf16 v[66:69], v[202:205], v[130:133], v[66:69]
	ds_read_b64_tr_b16 v[204:205], v163 offset:42496
	ds_read_b64_tr_b16 v[202:203], v163 offset:33792
	v_pk_mul_f32 v[74:75], v[74:75], v[64:65] op_sel_hi:[1,0]
	s_waitcnt lgkmcnt(2)
	v_mfma_f32_16x16x32_bf16 v[66:69], v[206:209], v[134:137], v[66:69]
	ds_read_b64_tr_b16 v[206:207], v163 offset:51200
	ds_read_b64_tr_b16 v[208:209], v163 offset:59904
	ds_read_b64_tr_b16 v[210:211], v163 offset:33856
	s_waitcnt lgkmcnt(3)
	v_mfma_f32_16x16x32_bf16 v[74:77], v[202:205], v[130:133], v[74:77]
	ds_read_b64_tr_b16 v[212:213], v163 offset:42560
	ds_read_b64_tr_b16 v[214:215], v163 offset:51264
	ds_read_b64_tr_b16 v[216:217], v163 offset:59968
	ds_read_b64_tr_b16 v[218:219], v163 offset:33888
	ds_read_b64_tr_b16 v[202:203], v163 offset:51296
	ds_read_b64_tr_b16 v[204:205], v163 offset:60000
	s_waitcnt lgkmcnt(7)
	v_mfma_f32_16x16x32_bf16 v[74:77], v[206:209], v[134:137], v[74:77]
	v_mul_f32_e64 v116, v116, v64
	v_mul_f32_e64 v117, v117, v64
	v_pk_mul_f32 v[114:115], v[114:115], v[64:65] op_sel_hi:[1,0]
	v_pk_mul_f32 v[112:113], v[112:113], v[64:65] op_sel_hi:[1,0]
	v_pk_mul_f32 v[110:111], v[110:111], v[64:65] op_sel_hi:[1,0]
	v_pk_mul_f32 v[108:109], v[108:109], v[64:65] op_sel_hi:[1,0]
	v_pk_mul_f32 v[106:107], v[106:107], v[64:65] op_sel_hi:[1,0]
	v_pk_mul_f32 v[84:85], v[84:85], v[64:65] op_sel_hi:[1,0]
	v_pk_mul_f32 v[82:83], v[82:83], v[64:65] op_sel_hi:[1,0]
	v_pk_mul_f32 v[88:89], v[88:89], v[64:65] op_sel_hi:[1,0]
	v_pk_mul_f32 v[86:87], v[86:87], v[64:65] op_sel_hi:[1,0]
	v_pk_mul_f32 v[80:81], v[80:81], v[64:65] op_sel_hi:[1,0]
	v_pk_mul_f32 v[78:79], v[78:79], v[64:65] op_sel_hi:[1,0]
	v_pk_mul_f32 v[96:97], v[96:97], v[64:65] op_sel_hi:[1,0]
	v_pk_mul_f32 v[94:95], v[94:95], v[64:65] op_sel_hi:[1,0]
	v_pk_mul_f32 v[92:93], v[92:93], v[64:65] op_sel_hi:[1,0]
	v_pk_mul_f32 v[90:91], v[90:91], v[64:65] op_sel_hi:[1,0]
	v_pk_mul_f32 v[104:105], v[104:105], v[64:65] op_sel_hi:[1,0]
	v_pk_mul_f32 v[102:103], v[102:103], v[64:65] op_sel_hi:[1,0]
	v_pk_mul_f32 v[100:101], v[100:101], v[64:65] op_sel_hi:[1,0]
	v_pk_mul_f32 v[98:99], v[98:99], v[64:65] op_sel_hi:[1,0]
	v_pk_mul_f32 v[120:121], v[120:121], v[64:65] op_sel_hi:[1,0]
	v_pk_mul_f32 v[118:119], v[118:119], v[64:65] op_sel_hi:[1,0]
	v_pk_mul_f32 v[124:125], v[124:125], v[64:65] op_sel_hi:[1,0]
	v_pk_mul_f32 v[122:123], v[122:123], v[64:65] op_sel_hi:[1,0]
	v_pk_mul_f32 v[128:129], v[128:129], v[64:65] op_sel_hi:[1,0]
	v_pk_mul_f32 v[126:127], v[126:127], v[64:65] op_sel_hi:[1,0]
	v_pk_mul_f32 v[72:73], v[72:73], v[64:65] op_sel_hi:[1,0]
	v_pk_mul_f32 v[70:71], v[70:71], v[64:65] op_sel_hi:[1,0]
	s_waitcnt lgkmcnt(5)
	v_mfma_f32_16x16x32_bf16 v[114:117], v[210:213], v[130:133], v[114:117]
	ds_read_b64_tr_b16 v[208:209], v163 offset:42624
	ds_read_b64_tr_b16 v[210:211], v163 offset:51328
	ds_read_b64_tr_b16 v[212:213], v163 offset:60032
	ds_read_b64_tr_b16 v[206:207], v163 offset:33920
	ds_read_b64_tr_b16 v[222:223], v163 offset:33952
	ds_read_b64_tr_b16 v[224:225], v163 offset:42656
	ds_read_b64_tr_b16 v[226:227], v163 offset:51360
	ds_read_b64_tr_b16 v[228:229], v163 offset:60064
	s_waitcnt lgkmcnt(10)
	v_mfma_f32_16x16x32_bf16 v[110:113], v[218:221], v[130:133], v[110:113]
	v_mfma_f32_16x16x32_bf16 v[114:117], v[214:217], v[134:137], v[114:117]
	s_waitcnt lgkmcnt(8)
	v_mfma_f32_16x16x32_bf16 v[110:113], v[202:205], v[134:137], v[110:113]
	s_waitcnt lgkmcnt(4)
	v_mfma_f32_16x16x32_bf16 v[106:109], v[206:209], v[130:133], v[106:109]
	ds_read_b64_tr_b16 v[204:205], v163 offset:42688
	ds_read_b64_tr_b16 v[206:207], v163 offset:51392
	ds_read_b64_tr_b16 v[208:209], v163 offset:60096
	ds_read_b64_tr_b16 v[202:203], v163 offset:33984
	ds_read_b64_tr_b16 v[214:215], v163 offset:34016
	ds_read_b64_tr_b16 v[216:217], v163 offset:42720
	ds_read_b64_tr_b16 v[218:219], v163 offset:51424
	ds_read_b64_tr_b16 v[220:221], v163 offset:60128
	s_waitcnt lgkmcnt(10)
	v_mfma_f32_16x16x32_bf16 v[82:85], v[222:225], v[130:133], v[82:85]
	v_mfma_f32_16x16x32_bf16 v[106:109], v[210:213], v[134:137], v[106:109]
	s_waitcnt lgkmcnt(8)
	v_mfma_f32_16x16x32_bf16 v[82:85], v[226:229], v[134:137], v[82:85]
	s_waitcnt lgkmcnt(4)
	v_mfma_f32_16x16x32_bf16 v[86:89], v[202:205], v[130:133], v[86:89]
	ds_read_b64_tr_b16 v[204:205], v163 offset:42752
	ds_read_b64_tr_b16 v[210:211], v163 offset:51456
	ds_read_b64_tr_b16 v[212:213], v163 offset:60160
	ds_read_b64_tr_b16 v[202:203], v163 offset:34048
	ds_read_b64_tr_b16 v[222:223], v163 offset:34080
	ds_read_b64_tr_b16 v[224:225], v163 offset:42784
	ds_read_b64_tr_b16 v[226:227], v163 offset:51488
	ds_read_b64_tr_b16 v[228:229], v163 offset:60192
	s_waitcnt lgkmcnt(10)
	v_mfma_f32_16x16x32_bf16 v[78:81], v[214:217], v[130:133], v[78:81]
	v_mfma_f32_16x16x32_bf16 v[86:89], v[206:209], v[134:137], v[86:89]
	s_waitcnt lgkmcnt(8)
	v_mfma_f32_16x16x32_bf16 v[78:81], v[218:221], v[134:137], v[78:81]
	s_waitcnt lgkmcnt(4)
	v_mfma_f32_16x16x32_bf16 v[94:97], v[202:205], v[130:133], v[94:97]
	ds_read_b64_tr_b16 v[204:205], v163 offset:42816
	ds_read_b64_tr_b16 v[206:207], v163 offset:51520
	ds_read_b64_tr_b16 v[208:209], v163 offset:60224
	ds_read_b64_tr_b16 v[202:203], v163 offset:34112
	ds_read_b64_tr_b16 v[214:215], v163 offset:34144
	ds_read_b64_tr_b16 v[216:217], v163 offset:42848
	ds_read_b64_tr_b16 v[218:219], v163 offset:51552
	ds_read_b64_tr_b16 v[220:221], v163 offset:60256
	s_waitcnt lgkmcnt(10)
	v_mfma_f32_16x16x32_bf16 v[90:93], v[222:225], v[130:133], v[90:93]
	v_mfma_f32_16x16x32_bf16 v[94:97], v[210:213], v[134:137], v[94:97]
	s_waitcnt lgkmcnt(8)
	v_mfma_f32_16x16x32_bf16 v[90:93], v[226:229], v[134:137], v[90:93]
	s_waitcnt lgkmcnt(4)
	v_mfma_f32_16x16x32_bf16 v[102:105], v[202:205], v[130:133], v[102:105]
	ds_read_b64_tr_b16 v[204:205], v163 offset:42880
	ds_read_b64_tr_b16 v[210:211], v163 offset:51584
	ds_read_b64_tr_b16 v[212:213], v163 offset:60288
	ds_read_b64_tr_b16 v[202:203], v163 offset:34176
	ds_read_b64_tr_b16 v[222:223], v163 offset:34208
	ds_read_b64_tr_b16 v[224:225], v163 offset:42912
	ds_read_b64_tr_b16 v[226:227], v163 offset:51616
	ds_read_b64_tr_b16 v[228:229], v163 offset:60320
	s_waitcnt lgkmcnt(10)
	v_mfma_f32_16x16x32_bf16 v[98:101], v[214:217], v[130:133], v[98:101]
	v_mfma_f32_16x16x32_bf16 v[102:105], v[206:209], v[134:137], v[102:105]
	s_waitcnt lgkmcnt(8)
	v_mfma_f32_16x16x32_bf16 v[98:101], v[218:221], v[134:137], v[98:101]
	s_waitcnt lgkmcnt(4)
	v_mfma_f32_16x16x32_bf16 v[118:121], v[202:205], v[130:133], v[118:121]
	ds_read_b64_tr_b16 v[204:205], v163 offset:42944
	ds_read_b64_tr_b16 v[206:207], v163 offset:51648
	ds_read_b64_tr_b16 v[208:209], v163 offset:60352
	ds_read_b64_tr_b16 v[202:203], v163 offset:34240
	ds_read_b64_tr_b16 v[214:215], v163 offset:34272
	ds_read_b64_tr_b16 v[216:217], v163 offset:42976
	ds_read_b64_tr_b16 v[218:219], v163 offset:51680
	ds_read_b64_tr_b16 v[220:221], v163 offset:60384
	s_waitcnt lgkmcnt(10)
	v_mfma_f32_16x16x32_bf16 v[122:125], v[222:225], v[130:133], v[122:125]
	v_mfma_f32_16x16x32_bf16 v[118:121], v[210:213], v[134:137], v[118:121]
	s_waitcnt lgkmcnt(8)
	v_mfma_f32_16x16x32_bf16 v[122:125], v[226:229], v[134:137], v[122:125]
	s_waitcnt lgkmcnt(4)
	v_mfma_f32_16x16x32_bf16 v[126:129], v[202:205], v[130:133], v[126:129]
	s_waitcnt lgkmcnt(2)
	v_mfma_f32_16x16x32_bf16 v[70:73], v[214:217], v[130:133], v[70:73]
	v_mfma_f32_16x16x32_bf16 v[126:129], v[206:209], v[134:137], v[126:129]
	s_waitcnt lgkmcnt(0)
	v_mfma_f32_16x16x32_bf16 v[70:73], v[218:221], v[134:137], v[70:73]
	s_add_u32 s30, s30, 0x40000
	s_addc_u32 s31, s31, 0
	s_cmp_lg_u32 s30, 0x100000
	s_cbranch_scc0 .LBB0_1433
	v_mov_b32_e32 v131, v200
	v_mov_b32_e32 v130, v201
	s_branch .LBB0_1429

.LBB0_1436:
	ds_read_b128 v[132:135], v199
	ds_read_b128 v[200:203], v199 offset:64
	ds_read_b128 v[204:207], v199 offset:128
	ds_read_b128 v[208:211], v199 offset:192
	ds_read_b128 v[212:215], v199 offset:384
	ds_read_b128 v[216:219], v199 offset:448
	s_waitcnt lgkmcnt(5)
	v_mfma_f32_16x16x32_bf16 v[132:135], v[132:135], v[0:3], 0
	s_waitcnt lgkmcnt(4)
	v_mfma_f32_16x16x32_bf16 v[132:135], v[200:203], v[4:7], v[132:135]
	ds_read_b128 v[200:203], v199 offset:256
	s_waitcnt lgkmcnt(4)
	v_mfma_f32_16x16x32_bf16 v[132:135], v[204:207], v[8:11], v[132:135]
	ds_read_b128 v[204:207], v199 offset:320
	s_waitcnt lgkmcnt(4)
	v_mfma_f32_16x16x32_bf16 v[132:135], v[208:211], v[12:15], v[132:135]
	s_waitcnt lgkmcnt(1)
	v_mfma_f32_16x16x32_bf16 v[132:135], v[200:203], v[16:19], v[132:135]
	ds_read_b128 v[200:203], v199 offset:8448
	ds_read_b128 v[208:211], v199 offset:8512
	ds_read_b128 v[220:223], v199 offset:8576
	ds_read_b128 v[224:227], v199 offset:8640
	s_waitcnt lgkmcnt(4)
	v_mfma_f32_16x16x32_bf16 v[132:135], v[204:207], v[20:23], v[132:135]
	v_mfma_f32_16x16x32_bf16 v[132:135], v[212:215], v[24:27], v[132:135]
	v_mfma_f32_16x16x32_bf16 v[132:135], v[216:219], v[28:31], v[132:135]
	s_waitcnt lgkmcnt(3)
	v_mfma_f32_16x16x32_bf16 v[200:203], v[200:203], v[0:3], 0
	ds_read_b128 v[204:207], v199 offset:8704
	ds_read_b128 v[212:215], v199 offset:8768
	ds_read_b128 v[216:219], v199 offset:8832
	ds_read_b128 v[228:231], v199 offset:8896
	s_waitcnt lgkmcnt(6)
	v_mfma_f32_16x16x32_bf16 v[200:203], v[208:211], v[4:7], v[200:203]
	s_waitcnt lgkmcnt(5)
	v_mfma_f32_16x16x32_bf16 v[200:203], v[220:223], v[8:11], v[200:203]
	s_waitcnt lgkmcnt(4)
	v_mfma_f32_16x16x32_bf16 v[200:203], v[224:227], v[12:15], v[200:203]
	s_waitcnt lgkmcnt(3)
	v_mfma_f32_16x16x32_bf16 v[200:203], v[204:207], v[16:19], v[200:203]
	ds_read_b128 v[204:207], v199 offset:16896
	ds_read_b128 v[208:211], v199 offset:16960
	ds_read_b128 v[220:223], v199 offset:17024
	ds_read_b128 v[224:227], v199 offset:17088
	s_waitcnt lgkmcnt(6)
	v_mfma_f32_16x16x32_bf16 v[200:203], v[212:215], v[20:23], v[200:203]
	s_waitcnt lgkmcnt(5)
	v_mfma_f32_16x16x32_bf16 v[200:203], v[216:219], v[24:27], v[200:203]
	s_waitcnt lgkmcnt(4)
	v_mfma_f32_16x16x32_bf16 v[212:215], v[228:231], v[28:31], v[200:203]
	s_waitcnt lgkmcnt(3)
	v_mfma_f32_16x16x32_bf16 v[200:203], v[204:207], v[0:3], 0
	ds_read_b128 v[204:207], v199 offset:17152
	ds_read_b128 v[216:219], v199 offset:17216
	ds_read_b128 v[228:231], v199 offset:17280
	ds_read_b128 v[232:235], v199 offset:17344
	s_waitcnt lgkmcnt(6)
	v_mfma_f32_16x16x32_bf16 v[200:203], v[208:211], v[4:7], v[200:203]
	s_waitcnt lgkmcnt(5)
	v_mfma_f32_16x16x32_bf16 v[200:203], v[220:223], v[8:11], v[200:203]
	s_waitcnt lgkmcnt(4)
	v_mfma_f32_16x16x32_bf16 v[200:203], v[224:227], v[12:15], v[200:203]
	s_waitcnt lgkmcnt(3)
	v_mfma_f32_16x16x32_bf16 v[200:203], v[204:207], v[16:19], v[200:203]
	ds_read_b128 v[204:207], v199 offset:25344
	ds_read_b128 v[208:211], v199 offset:25408
	ds_read_b128 v[220:223], v199 offset:25472
	ds_read_b128 v[224:227], v199 offset:25536
	s_waitcnt lgkmcnt(6)
	v_mfma_f32_16x16x32_bf16 v[200:203], v[216:219], v[20:23], v[200:203]
	s_waitcnt lgkmcnt(5)
	v_mfma_f32_16x16x32_bf16 v[200:203], v[228:231], v[24:27], v[200:203]
	s_waitcnt lgkmcnt(4)
	v_mfma_f32_16x16x32_bf16 v[216:219], v[232:235], v[28:31], v[200:203]
	s_waitcnt lgkmcnt(3)
	v_mfma_f32_16x16x32_bf16 v[200:203], v[204:207], v[0:3], 0
	ds_read_b128 v[204:207], v199 offset:25600
	ds_read_b128 v[228:231], v199 offset:25664
	ds_read_b128 v[232:235], v199 offset:25728
	ds_read_b128 v[236:239], v199 offset:25792
	s_waitcnt lgkmcnt(6)
	v_mfma_f32_16x16x32_bf16 v[200:203], v[208:211], v[4:7], v[200:203]
	s_waitcnt lgkmcnt(5)
	v_mfma_f32_16x16x32_bf16 v[200:203], v[220:223], v[8:11], v[200:203]
	s_waitcnt lgkmcnt(4)
	v_mfma_f32_16x16x32_bf16 v[200:203], v[224:227], v[12:15], v[200:203]
	s_waitcnt lgkmcnt(3)
	v_mfma_f32_16x16x32_bf16 v[200:203], v[204:207], v[16:19], v[200:203]
	s_waitcnt lgkmcnt(2)
	v_mfma_f32_16x16x32_bf16 v[200:203], v[228:231], v[20:23], v[200:203]
	s_waitcnt lgkmcnt(1)
	v_mfma_f32_16x16x32_bf16 v[200:203], v[232:235], v[24:27], v[200:203]
	s_waitcnt lgkmcnt(0)
	v_mfma_f32_16x16x32_bf16 v[202:205], v[236:239], v[28:31], v[200:203]
	v_max3_f32 v64, v132, s33, v133
	v_max3_f32 v64, v64, v134, v135
	v_max3_f32 v64, v64, v212, v213
	v_max3_f32 v64, v64, v214, v215
	v_max3_f32 v64, v64, v216, v217
	v_max3_f32 v64, v64, v218, v219
	s_nop 1
	v_max3_f32 v64, v64, v202, v203
	v_max3_f32 v64, v64, v204, v205
	ds_bpermute_b32 v136, v148, v64
	ds_read_b64_tr_b16 v[220:221], v163 offset:42592
	s_waitcnt lgkmcnt(1)
	v_max_f32_e32 v136, v136, v136
	v_max_f32_e32 v64, v64, v136
	ds_bpermute_b32 v136, v149, v64
	s_waitcnt lgkmcnt(0)
	v_max3_f32 v200, v131, v64, v136
	v_cmp_neq_f32_e32 vcc, s33, v200
	s_nop 1
	v_cndmask_b32_e32 v136, 0, v200, vcc
	v_sub_f32_e32 v201, v213, v136
	v_exp_f32_e32 v206, v201
	v_sub_f32_e32 v201, v214, v136
	v_sub_f32_e32 v64, v131, v136
	v_sub_f32_e32 v131, v132, v136
	v_exp_f32_e32 v207, v201
	v_sub_f32_e32 v201, v215, v136
	v_sub_f32_e32 v132, v133, v136
	v_sub_f32_e32 v133, v134, v136
	v_exp_f32_e32 v131, v131
	v_exp_f32_e32 v208, v201
	v_sub_f32_e32 v201, v216, v136
	v_exp_f32_e32 v132, v132
	v_sub_f32_e32 v134, v135, v136
	v_exp_f32_e32 v133, v133
	v_sub_f32_e32 v137, v212, v136
	v_exp_f32_e32 v209, v201
	v_sub_f32_e32 v201, v217, v136
	v_exp_f32_e32 v134, v134
	v_add_f32_e32 v135, 0, v131
	v_exp_f32_e32 v137, v137
	v_exp_f32_e32 v210, v201
	v_sub_f32_e32 v201, v218, v136
	v_add_f32_e32 v135, v132, v135
	v_add_f32_e32 v135, v133, v135
	v_exp_f32_e32 v211, v201
	v_sub_f32_e32 v201, v219, v136
	v_add_f32_e32 v135, v134, v135
	v_add_f32_e32 v135, v137, v135
	v_exp_f32_e32 v212, v201
	v_sub_f32_e32 v201, v202, v136
	v_add_f32_e32 v135, v206, v135
	v_add_f32_e32 v135, v207, v135
	v_exp_f32_e32 v202, v201
	v_sub_f32_e32 v201, v203, v136
	v_add_f32_e32 v135, v208, v135
	v_add_f32_e32 v135, v209, v135
	v_exp_f32_e32 v203, v201
	v_sub_f32_e32 v201, v204, v136
	v_add_f32_e32 v135, v210, v135
	v_sub_f32_e32 v136, v205, v136
	v_add_f32_e32 v135, v211, v135
	v_exp_f32_e32 v204, v201
	v_add_f32_e32 v135, v212, v135
	v_exp_f32_e32 v205, v136
	v_exp_f32_e32 v64, v64
	v_add_f32_e32 v135, v202, v135
	v_add_f32_e32 v135, v203, v135
	v_add_f32_e32 v135, v204, v135
	v_add_f32_e32 v201, v205, v135
	v_fmac_f32_e32 v201, v130, v64
	v_cvt_pk_bf16_f32 v130, v131, v132
	v_cvt_pk_bf16_f32 v132, v137, v206
	v_cvt_pk_bf16_f32 v136, v202, v203
	v_cvt_pk_bf16_f32 v137, v204, v205
	ds_read_b64_tr_b16 v[202:203], v163 offset:33824
	ds_read_b64_tr_b16 v[204:205], v163 offset:42528
	v_cvt_pk_bf16_f32 v131, v133, v134
	v_cvt_pk_bf16_f32 v133, v207, v208
	v_cvt_pk_bf16_f32 v134, v209, v210
	ds_read_b64_tr_b16 v[206:207], v163 offset:51232
	ds_read_b64_tr_b16 v[208:209], v163 offset:59936
	v_pk_mul_f32 v[68:69], v[68:69], v[64:65] op_sel_hi:[1,0]
	v_pk_mul_f32 v[66:67], v[66:67], v[64:65] op_sel_hi:[1,0]
	v_cvt_pk_bf16_f32 v135, v211, v212
	v_pk_mul_f32 v[80:81], v[80:81], v[64:65] op_sel_hi:[1,0]
	s_waitcnt lgkmcnt(2)
	v_mfma_f32_16x16x32_bf16 v[66:69], v[202:205], v[130:133], v[66:69]
	ds_read_b64_tr_b16 v[204:205], v163 offset:42496
	ds_read_b64_tr_b16 v[202:203], v163 offset:33792
	v_pk_mul_f32 v[78:79], v[78:79], v[64:65] op_sel_hi:[1,0]
	s_waitcnt lgkmcnt(2)
	v_mfma_f32_16x16x32_bf16 v[66:69], v[206:209], v[134:137], v[66:69]
	ds_read_b64_tr_b16 v[206:207], v163 offset:51200
	ds_read_b64_tr_b16 v[208:209], v163 offset:59904
	ds_read_b64_tr_b16 v[210:211], v163 offset:33856
	s_waitcnt lgkmcnt(3)
	v_mfma_f32_16x16x32_bf16 v[78:81], v[202:205], v[130:133], v[78:81]
	ds_read_b64_tr_b16 v[212:213], v163 offset:42560
	ds_read_b64_tr_b16 v[214:215], v163 offset:51264
	ds_read_b64_tr_b16 v[216:217], v163 offset:59968
	ds_read_b64_tr_b16 v[218:219], v163 offset:33888
	ds_read_b64_tr_b16 v[202:203], v163 offset:51296
	ds_read_b64_tr_b16 v[204:205], v163 offset:60000
	s_waitcnt lgkmcnt(7)
	v_mfma_f32_16x16x32_bf16 v[78:81], v[206:209], v[134:137], v[78:81]
	v_mul_f32_e64 v116, v116, v64
	v_mul_f32_e64 v117, v117, v64
	v_pk_mul_f32 v[114:115], v[114:115], v[64:65] op_sel_hi:[1,0]
	v_pk_mul_f32 v[112:113], v[112:113], v[64:65] op_sel_hi:[1,0]
	v_pk_mul_f32 v[110:111], v[110:111], v[64:65] op_sel_hi:[1,0]
	v_pk_mul_f32 v[108:109], v[108:109], v[64:65] op_sel_hi:[1,0]
	v_pk_mul_f32 v[106:107], v[106:107], v[64:65] op_sel_hi:[1,0]
	v_pk_mul_f32 v[84:85], v[84:85], v[64:65] op_sel_hi:[1,0]
	v_pk_mul_f32 v[82:83], v[82:83], v[64:65] op_sel_hi:[1,0]
	v_pk_mul_f32 v[88:89], v[88:89], v[64:65] op_sel_hi:[1,0]
	v_pk_mul_f32 v[86:87], v[86:87], v[64:65] op_sel_hi:[1,0]
	v_pk_mul_f32 v[76:77], v[76:77], v[64:65] op_sel_hi:[1,0]
	v_pk_mul_f32 v[74:75], v[74:75], v[64:65] op_sel_hi:[1,0]
	v_pk_mul_f32 v[96:97], v[96:97], v[64:65] op_sel_hi:[1,0]
	v_pk_mul_f32 v[94:95], v[94:95], v[64:65] op_sel_hi:[1,0]
	v_pk_mul_f32 v[92:93], v[92:93], v[64:65] op_sel_hi:[1,0]
	v_pk_mul_f32 v[90:91], v[90:91], v[64:65] op_sel_hi:[1,0]
	v_pk_mul_f32 v[104:105], v[104:105], v[64:65] op_sel_hi:[1,0]
	v_pk_mul_f32 v[102:103], v[102:103], v[64:65] op_sel_hi:[1,0]
	v_pk_mul_f32 v[100:101], v[100:101], v[64:65] op_sel_hi:[1,0]
	v_pk_mul_f32 v[98:99], v[98:99], v[64:65] op_sel_hi:[1,0]
	v_pk_mul_f32 v[120:121], v[120:121], v[64:65] op_sel_hi:[1,0]
	v_pk_mul_f32 v[118:119], v[118:119], v[64:65] op_sel_hi:[1,0]
	v_pk_mul_f32 v[124:125], v[124:125], v[64:65] op_sel_hi:[1,0]
	v_pk_mul_f32 v[122:123], v[122:123], v[64:65] op_sel_hi:[1,0]
	v_pk_mul_f32 v[128:129], v[128:129], v[64:65] op_sel_hi:[1,0]
	v_pk_mul_f32 v[126:127], v[126:127], v[64:65] op_sel_hi:[1,0]
	v_pk_mul_f32 v[72:73], v[72:73], v[64:65] op_sel_hi:[1,0]
	v_pk_mul_f32 v[70:71], v[70:71], v[64:65] op_sel_hi:[1,0]
	s_waitcnt lgkmcnt(5)
	v_mfma_f32_16x16x32_bf16 v[114:117], v[210:213], v[130:133], v[114:117]
	ds_read_b64_tr_b16 v[208:209], v163 offset:42624
	ds_read_b64_tr_b16 v[210:211], v163 offset:51328
	ds_read_b64_tr_b16 v[212:213], v163 offset:60032
	ds_read_b64_tr_b16 v[206:207], v163 offset:33920
	ds_read_b64_tr_b16 v[222:223], v163 offset:33952
	ds_read_b64_tr_b16 v[224:225], v163 offset:42656
	ds_read_b64_tr_b16 v[226:227], v163 offset:51360
	ds_read_b64_tr_b16 v[228:229], v163 offset:60064
	s_waitcnt lgkmcnt(10)
	v_mfma_f32_16x16x32_bf16 v[110:113], v[218:221], v[130:133], v[110:113]
	v_mfma_f32_16x16x32_bf16 v[114:117], v[214:217], v[134:137], v[114:117]
	s_waitcnt lgkmcnt(8)
	v_mfma_f32_16x16x32_bf16 v[110:113], v[202:205], v[134:137], v[110:113]
	s_waitcnt lgkmcnt(4)
	v_mfma_f32_16x16x32_bf16 v[106:109], v[206:209], v[130:133], v[106:109]
	ds_read_b64_tr_b16 v[204:205], v163 offset:42688
	ds_read_b64_tr_b16 v[206:207], v163 offset:51392
	ds_read_b64_tr_b16 v[208:209], v163 offset:60096
	ds_read_b64_tr_b16 v[202:203], v163 offset:33984
	ds_read_b64_tr_b16 v[214:215], v163 offset:34016
	ds_read_b64_tr_b16 v[216:217], v163 offset:42720
	ds_read_b64_tr_b16 v[218:219], v163 offset:51424
	ds_read_b64_tr_b16 v[220:221], v163 offset:60128
	s_waitcnt lgkmcnt(10)
	v_mfma_f32_16x16x32_bf16 v[82:85], v[222:225], v[130:133], v[82:85]
	v_mfma_f32_16x16x32_bf16 v[106:109], v[210:213], v[134:137], v[106:109]
	s_waitcnt lgkmcnt(8)
	v_mfma_f32_16x16x32_bf16 v[82:85], v[226:229], v[134:137], v[82:85]
	s_waitcnt lgkmcnt(4)
	v_mfma_f32_16x16x32_bf16 v[86:89], v[202:205], v[130:133], v[86:89]
	ds_read_b64_tr_b16 v[204:205], v163 offset:42752
	ds_read_b64_tr_b16 v[210:211], v163 offset:51456
	ds_read_b64_tr_b16 v[212:213], v163 offset:60160
	ds_read_b64_tr_b16 v[202:203], v163 offset:34048
	ds_read_b64_tr_b16 v[222:223], v163 offset:34080
	ds_read_b64_tr_b16 v[224:225], v163 offset:42784
	ds_read_b64_tr_b16 v[226:227], v163 offset:51488
	ds_read_b64_tr_b16 v[228:229], v163 offset:60192
	s_waitcnt lgkmcnt(10)
	v_mfma_f32_16x16x32_bf16 v[74:77], v[214:217], v[130:133], v[74:77]
	v_mfma_f32_16x16x32_bf16 v[86:89], v[206:209], v[134:137], v[86:89]
	s_waitcnt lgkmcnt(8)
	v_mfma_f32_16x16x32_bf16 v[74:77], v[218:221], v[134:137], v[74:77]
	s_waitcnt lgkmcnt(4)
	v_mfma_f32_16x16x32_bf16 v[94:97], v[202:205], v[130:133], v[94:97]
	ds_read_b64_tr_b16 v[204:205], v163 offset:42816
	ds_read_b64_tr_b16 v[206:207], v163 offset:51520
	ds_read_b64_tr_b16 v[208:209], v163 offset:60224
	ds_read_b64_tr_b16 v[202:203], v163 offset:34112
	ds_read_b64_tr_b16 v[214:215], v163 offset:34144
	ds_read_b64_tr_b16 v[216:217], v163 offset:42848
	ds_read_b64_tr_b16 v[218:219], v163 offset:51552
	ds_read_b64_tr_b16 v[220:221], v163 offset:60256
	s_waitcnt lgkmcnt(10)
	v_mfma_f32_16x16x32_bf16 v[90:93], v[222:225], v[130:133], v[90:93]
	v_mfma_f32_16x16x32_bf16 v[94:97], v[210:213], v[134:137], v[94:97]
	s_waitcnt lgkmcnt(8)
	v_mfma_f32_16x16x32_bf16 v[90:93], v[226:229], v[134:137], v[90:93]
	s_waitcnt lgkmcnt(4)
	v_mfma_f32_16x16x32_bf16 v[102:105], v[202:205], v[130:133], v[102:105]
	ds_read_b64_tr_b16 v[204:205], v163 offset:42880
	ds_read_b64_tr_b16 v[210:211], v163 offset:51584
	ds_read_b64_tr_b16 v[212:213], v163 offset:60288
	ds_read_b64_tr_b16 v[202:203], v163 offset:34176
	ds_read_b64_tr_b16 v[222:223], v163 offset:34208
	ds_read_b64_tr_b16 v[224:225], v163 offset:42912
	ds_read_b64_tr_b16 v[226:227], v163 offset:51616
	ds_read_b64_tr_b16 v[228:229], v163 offset:60320
	s_waitcnt lgkmcnt(10)
	v_mfma_f32_16x16x32_bf16 v[98:101], v[214:217], v[130:133], v[98:101]
	v_mfma_f32_16x16x32_bf16 v[102:105], v[206:209], v[134:137], v[102:105]
	s_waitcnt lgkmcnt(8)
	v_mfma_f32_16x16x32_bf16 v[98:101], v[218:221], v[134:137], v[98:101]
	s_waitcnt lgkmcnt(4)
	v_mfma_f32_16x16x32_bf16 v[118:121], v[202:205], v[130:133], v[118:121]
	ds_read_b64_tr_b16 v[204:205], v163 offset:42944
	ds_read_b64_tr_b16 v[206:207], v163 offset:51648
	ds_read_b64_tr_b16 v[208:209], v163 offset:60352
	ds_read_b64_tr_b16 v[202:203], v163 offset:34240
	ds_read_b64_tr_b16 v[214:215], v163 offset:34272
	ds_read_b64_tr_b16 v[216:217], v163 offset:42976
	ds_read_b64_tr_b16 v[218:219], v163 offset:51680
	ds_read_b64_tr_b16 v[220:221], v163 offset:60384
	s_waitcnt lgkmcnt(10)
	v_mfma_f32_16x16x32_bf16 v[122:125], v[222:225], v[130:133], v[122:125]
	v_mfma_f32_16x16x32_bf16 v[118:121], v[210:213], v[134:137], v[118:121]
	s_waitcnt lgkmcnt(8)
	v_mfma_f32_16x16x32_bf16 v[122:125], v[226:229], v[134:137], v[122:125]
	s_waitcnt lgkmcnt(4)
	v_mfma_f32_16x16x32_bf16 v[126:129], v[202:205], v[130:133], v[126:129]
	s_waitcnt lgkmcnt(2)
	v_mfma_f32_16x16x32_bf16 v[70:73], v[214:217], v[130:133], v[70:73]
	v_mfma_f32_16x16x32_bf16 v[126:129], v[206:209], v[134:137], v[126:129]
	s_waitcnt lgkmcnt(0)
	v_mfma_f32_16x16x32_bf16 v[70:73], v[218:221], v[134:137], v[70:73]
	s_add_u32 s0, s0, 0x40000
	s_addc_u32 s1, s1, 0
	s_cmp_lg_u32 s0, 0x100000
	s_cbranch_scc0 .LBB0_1409
	v_mov_b32_e32 v131, v200
	v_mov_b32_e32 v130, v201
	s_branch .LBB0_1434
